# address arithmetic: LDS-DMA tile loads take SGPR base + 32-bit VGPR offset (saddr form) instead of a v_lshl_add_u64 per load
# baseline (speedup 1.0000x reference)
.LBB0_391:
	s_add_u32 s4, s0, 0x2400000
	s_addc_u32 s5, s1, 0
	s_lshl_b32 s9, s14, 5
	s_and_b32 s9, s9, 0x60
	s_add_i32 m0, s42, 0x18000
	v_lshl_add_u64 v[8:9], v[8:9], 0, s[88:89]
	s_lshl_b32 s46, s7, 6
	s_lshl_b32 s7, s7, 13
	s_lshl_b32 s13, s9, 7
	s_waitcnt vmcnt(2)
	s_barrier
	global_load_lds_dwordx4 v[8:9], off
	v_lshl_add_u64 v[6:7], v[6:7], 0, s[88:89]
	s_add_i32 m0, s42, 0x1a000
	s_add_i32 s47, s42, 0x8000
	s_add_i32 s48, s42, 0xa000
	global_load_lds_dwordx4 v[6:7], off
	v_lshl_add_u64 v[2:3], v[2:3], 0, s[88:89]
	s_mov_b32 m0, s47
	s_add_u32 s14, s24, 0x40080
	global_load_lds_dwordx4 v[2:3], off
	v_lshl_add_u64 v[2:3], v[4:5], 0, s[88:89]
	s_mov_b32 m0, s48
	s_addc_u32 s15, s25, 0
	global_load_lds_dwordx4 v[2:3], off
	s_add_i32 m0, s42, 0x1c000
	s_nop 0
	global_load_lds_dwordx4 v132, s[14:15]
	v_lshl_add_u64 v[2:3], s[14:15], 0, v[136:137]
	s_add_i32 m0, s42, 0x1e000
	v_and_b32_e32 v141, 15, v0
	global_load_lds_dwordx4 v[2:3], off
	v_lshrrev_b32_e32 v2, 1, v0
	v_and_b32_e32 v2, 24, v2
	v_lshlrev_b32_e32 v3, 1, v2
	v_lshlrev_b32_e32 v4, 2, v0
	v_lshl_or_b32 v3, v141, 6, v3
	v_and_b32_e32 v4, 32, v4
	v_or_b32_e32 v138, s9, v2
	v_bitop3_b32 v145, s9, 56, v2 bitop3:0xc8
	v_bfe_u32 v2, v0, 2, 2
	v_bitop3_b32 v5, v3, s7, v4 bitop3:0xde
	v_bitop3_b32 v143, v3, s13, v4 bitop3:0xde
	v_and_b32_e32 v3, 12, v0
	v_cmp_ne_u32_e32 vcc, 2, v2
	v_or_b32_e32 v147, 16, v141
	v_or_b32_e32 v158, 32, v141
	v_cndmask_b32_e32 v3, 4, v3, vcc
	v_cmp_ne_u32_e32 vcc, 1, v2
	v_or_b32_e32 v159, 48, v141
	s_waitcnt vmcnt(6)
	s_cmpk_lt_u32 s6, 0x100
	v_cndmask_b32_e32 v2, 8, v3, vcc
	v_and_or_b32 v140, v0, 3, v2
	v_lshlrev_b32_e32 v0, 14, v10
	v_and_b32_e32 v0, 0xffff8000, v0
	v_and_or_b32 v142, v147, 19, v2
	v_and_or_b32 v144, v158, 35, v2
	v_and_or_b32 v146, v159, 51, v2
	v_lshl_add_u32 v0, v11, 11, v0
	v_and_b32_e32 v2, 1, v10
	v_lshl_or_b32 v0, v2, 6, v0
	v_lshl_add_u32 v148, v12, 1, v0
	v_lshlrev_b32_e32 v0, 14, v13
	v_and_b32_e32 v0, 0xffff8000, v0
	v_lshl_add_u32 v0, v14, 11, v0
	v_and_b32_e32 v2, 1, v13
	v_lshl_or_b32 v0, v2, 6, v0
	s_cselect_b64 s[14:15], -1, 0
	s_ashr_i32 s49, s36, 31
	s_ashr_i32 s50, s33, 31
	v_mov_b32_e32 v139, v1
	v_mov_b32_e32 v149, v1
	v_lshl_add_u32 v150, v15, 1, v0
	v_mov_b32_e32 v151, v1
	s_mov_b32 s51, 0
	v_add_u32_e32 v161, 0, v5
	s_barrier
	s_branch .LBB0_394

.LBB0_397:
	s_add_u32 s24, s10, 0xfffc0080
	s_addc_u32 s25, s11, -1
	s_add_i32 s31, 0, 0x10000
	s_cmp_eq_u32 s30, 12
	s_cselect_b32 s27, s9, s25
	s_cselect_b32 s26, s13, s24
	v_add_u32_e32 v0, s31, v143
	s_cselect_b32 s25, s17, s29
	s_cselect_b32 s24, s19, s28
	s_add_i32 s52, 0, 0x14000
	ds_read_b128 v[152:155], v0
	ds_read_b128 v[166:169], v0 offset:1024
	ds_read_b128 v[170:173], v0 offset:2048
	ds_read_b128 v[174:177], v0 offset:3072
	v_add_u32_e32 v0, s52, v143
	ds_read_b128 v[198:201], v0
	ds_read_b128 v[202:205], v0 offset:1024
	ds_read_b128 v[206:209], v0 offset:2048
	ds_read_b128 v[210:213], v0 offset:3072
	s_add_i32 m0, s42, 0xc000
	ds_read_b128 v[214:217], v161
	ds_read_b128 v[218:221], v161 offset:1024
	ds_read_b128 v[222:225], v161 offset:2048
	ds_read_b128 v[226:229], v161 offset:3072
	ds_read_b128 v[230:233], v161 offset:4096
	ds_read_b128 v[234:237], v161 offset:5120
	ds_read_b128 v[238:241], v161 offset:6144
	ds_read_b128 v[242:245], v161 offset:7168
	global_load_lds_dwordx4 v148, s[10:11]
	s_add_i32 m0, s42, 0xe000
	s_nop 0
	global_load_lds_dwordx4 v150, s[10:11]
	s_waitcnt vmcnt(8)
	s_waitcnt lgkmcnt(0)
	s_barrier
	s_setprio 1
	s_waitcnt lgkmcnt(0)
	v_mfma_f32_16x16x32_bf16 v[126:129], v[152:155], v[214:217], v[126:129]
	v_mfma_f32_16x16x32_bf16 v[122:125], v[170:173], v[214:217], v[122:125]
	v_mfma_f32_16x16x32_bf16 v[110:113], v[152:155], v[222:225], v[110:113]
	v_mfma_f32_16x16x32_bf16 v[106:109], v[170:173], v[222:225], v[106:109]
	v_mfma_f32_16x16x32_bf16 v[94:97], v[152:155], v[230:233], v[94:97]
	v_mfma_f32_16x16x32_bf16 v[90:93], v[170:173], v[230:233], v[90:93]
	v_mfma_f32_16x16x32_bf16 v[78:81], v[152:155], v[238:241], v[78:81]
	v_mfma_f32_16x16x32_bf16 v[74:77], v[170:173], v[238:241], v[74:77]
	v_mfma_f32_16x16x32_bf16 v[126:129], v[166:169], v[218:221], v[126:129]
	v_mfma_f32_16x16x32_bf16 v[122:125], v[174:177], v[218:221], v[122:125]
	v_mfma_f32_16x16x32_bf16 v[110:113], v[166:169], v[226:229], v[110:113]
	v_mfma_f32_16x16x32_bf16 v[106:109], v[174:177], v[226:229], v[106:109]
	v_mfma_f32_16x16x32_bf16 v[94:97], v[166:169], v[234:237], v[94:97]
	v_mfma_f32_16x16x32_bf16 v[90:93], v[174:177], v[234:237], v[90:93]
	v_mfma_f32_16x16x32_bf16 v[78:81], v[166:169], v[242:245], v[78:81]
	v_mfma_f32_16x16x32_bf16 v[74:77], v[174:177], v[242:245], v[74:77]
	s_setprio 0
	s_setprio 1
	v_mfma_f32_16x16x32_bf16 v[118:121], v[198:201], v[214:217], v[118:121]
	v_mfma_f32_16x16x32_bf16 v[114:117], v[206:209], v[214:217], v[114:117]
	v_mfma_f32_16x16x32_bf16 v[102:105], v[198:201], v[222:225], v[102:105]
	v_mfma_f32_16x16x32_bf16 v[98:101], v[206:209], v[222:225], v[98:101]
	v_mfma_f32_16x16x32_bf16 v[86:89], v[198:201], v[230:233], v[86:89]
	v_mfma_f32_16x16x32_bf16 v[82:85], v[206:209], v[230:233], v[82:85]
	v_mfma_f32_16x16x32_bf16 v[70:73], v[198:201], v[238:241], v[70:73]
	v_mfma_f32_16x16x32_bf16 v[66:69], v[206:209], v[238:241], v[66:69]
	v_mfma_f32_16x16x32_bf16 v[118:121], v[202:205], v[218:221], v[118:121]
	v_mfma_f32_16x16x32_bf16 v[114:117], v[210:213], v[218:221], v[114:117]
	v_mfma_f32_16x16x32_bf16 v[102:105], v[202:205], v[226:229], v[102:105]
	v_mfma_f32_16x16x32_bf16 v[98:101], v[210:213], v[226:229], v[98:101]
	v_mfma_f32_16x16x32_bf16 v[86:89], v[202:205], v[234:237], v[86:89]
	v_mfma_f32_16x16x32_bf16 v[82:85], v[210:213], v[234:237], v[82:85]
	v_mfma_f32_16x16x32_bf16 v[70:73], v[202:205], v[242:245], v[70:73]
	v_mfma_f32_16x16x32_bf16 v[66:69], v[210:213], v[242:245], v[66:69]
	s_setprio 0
	s_barrier
	s_add_i32 s31, s31, s41
	v_lshl_add_u64 v[156:157], s[24:25], 0, v[132:133]
	s_mov_b32 m0, s31
	ds_read_b128 v[214:217], v161 offset:16384
	ds_read_b128 v[218:221], v161 offset:17408
	ds_read_b128 v[222:225], v161 offset:18432
	ds_read_b128 v[226:229], v161 offset:19456
	ds_read_b128 v[230:233], v161 offset:20480
	ds_read_b128 v[234:237], v161 offset:21504
	ds_read_b128 v[238:241], v161 offset:22528
	ds_read_b128 v[242:245], v161 offset:23552
	global_load_lds_dwordx4 v[156:157], off
	s_add_i32 m0, s31, 0x2000
	s_add_u32 s34, s24, 0x40000
	v_lshl_add_u64 v[178:179], s[24:25], 0, v[136:137]
	s_addc_u32 s35, s25, 0
	s_add_i32 s31, s52, s41
	global_load_lds_dwordx4 v[178:179], off
	s_mov_b32 m0, s31
	v_lshl_add_u64 v[248:249], s[26:27], 0, v[134:135]
	global_load_lds_dwordx4 v132, s[34:35]
	s_add_i32 m0, s31, 0x2000
	s_nop 0
	global_load_lds_dwordx4 v136, s[34:35]
	v_lshl_add_u64 v[246:247], s[26:27], 0, v[130:131]
	s_mov_b32 m0, s42
	s_nop 0
	global_load_lds_dwordx4 v[246:247], off
	s_mov_b32 m0, s43
	s_nop 0
	global_load_lds_dwordx4 v[248:249], off
	s_waitcnt vmcnt(8)
	s_waitcnt lgkmcnt(0)
	s_barrier
	s_setprio 1
	s_waitcnt lgkmcnt(0)
	v_mfma_f32_16x16x32_bf16 v[62:65], v[152:155], v[214:217], v[62:65]
	v_mfma_f32_16x16x32_bf16 v[58:61], v[170:173], v[214:217], v[58:61]
	v_mfma_f32_16x16x32_bf16 v[46:49], v[152:155], v[222:225], v[46:49]
	v_mfma_f32_16x16x32_bf16 v[42:45], v[170:173], v[222:225], v[42:45]
	v_mfma_f32_16x16x32_bf16 v[30:33], v[152:155], v[230:233], v[30:33]
	v_mfma_f32_16x16x32_bf16 v[26:29], v[170:173], v[230:233], v[26:29]
	v_mfma_f32_16x16x32_bf16 v[14:17], v[152:155], v[238:241], v[14:17]
	v_mfma_f32_16x16x32_bf16 v[10:13], v[170:173], v[238:241], v[10:13]
	v_mfma_f32_16x16x32_bf16 v[62:65], v[166:169], v[218:221], v[62:65]
	v_mfma_f32_16x16x32_bf16 v[58:61], v[174:177], v[218:221], v[58:61]
	v_mfma_f32_16x16x32_bf16 v[46:49], v[166:169], v[226:229], v[46:49]
	v_mfma_f32_16x16x32_bf16 v[42:45], v[174:177], v[226:229], v[42:45]
	v_mfma_f32_16x16x32_bf16 v[30:33], v[166:169], v[234:237], v[30:33]
	v_mfma_f32_16x16x32_bf16 v[26:29], v[174:177], v[234:237], v[26:29]
	v_mfma_f32_16x16x32_bf16 v[14:17], v[166:169], v[242:245], v[14:17]
	v_mfma_f32_16x16x32_bf16 v[10:13], v[174:177], v[242:245], v[10:13]
	s_setprio 0
	s_setprio 1
	v_mfma_f32_16x16x32_bf16 v[54:57], v[198:201], v[214:217], v[54:57]
	v_mfma_f32_16x16x32_bf16 v[50:53], v[206:209], v[214:217], v[50:53]
	v_mfma_f32_16x16x32_bf16 v[38:41], v[198:201], v[222:225], v[38:41]
	v_mfma_f32_16x16x32_bf16 v[34:37], v[206:209], v[222:225], v[34:37]
	v_mfma_f32_16x16x32_bf16 v[22:25], v[198:201], v[230:233], v[22:25]
	v_mfma_f32_16x16x32_bf16 v[18:21], v[206:209], v[230:233], v[18:21]
	v_mfma_f32_16x16x32_bf16 v[6:9], v[198:201], v[238:241], v[6:9]
	v_mfma_f32_16x16x32_bf16 v[2:5], v[206:209], v[238:241], v[2:5]
	v_mfma_f32_16x16x32_bf16 v[54:57], v[202:205], v[218:221], v[54:57]
	v_mfma_f32_16x16x32_bf16 v[50:53], v[210:213], v[218:221], v[50:53]
	v_mfma_f32_16x16x32_bf16 v[38:41], v[202:205], v[226:229], v[38:41]
	v_mfma_f32_16x16x32_bf16 v[34:37], v[210:213], v[226:229], v[34:37]
	v_mfma_f32_16x16x32_bf16 v[22:25], v[202:205], v[234:237], v[22:25]
	v_mfma_f32_16x16x32_bf16 v[18:21], v[210:213], v[234:237], v[18:21]
	v_mfma_f32_16x16x32_bf16 v[6:9], v[202:205], v[242:245], v[6:9]
	v_mfma_f32_16x16x32_bf16 v[2:5], v[210:213], v[242:245], v[2:5]
	s_setprio 0
	s_barrier
	s_add_i32 s31, 0, 0x18000
	v_add_u32_e32 v0, s31, v143
	s_add_i32 s34, 0, 0x1c000
	ds_read_b128 v[152:155], v0
	ds_read_b128 v[166:169], v0 offset:1024
	ds_read_b128 v[170:173], v0 offset:2048
	ds_read_b128 v[174:177], v0 offset:3072
	v_add_u32_e32 v0, s34, v143
	ds_read_b128 v[198:201], v0
	ds_read_b128 v[202:205], v0 offset:1024
	ds_read_b128 v[206:209], v0 offset:2048
	ds_read_b128 v[210:213], v0 offset:3072
	s_add_u32 s26, s26, 0x40000
	s_addc_u32 s27, s27, 0
	s_mov_b32 m0, s44
	ds_read_b128 v[214:217], v161 offset:32768
	ds_read_b128 v[218:221], v161 offset:33792
	ds_read_b128 v[222:225], v161 offset:34816
	ds_read_b128 v[226:229], v161 offset:35840
	ds_read_b128 v[230:233], v161 offset:36864
	ds_read_b128 v[234:237], v161 offset:37888
	ds_read_b128 v[238:241], v161 offset:38912
	ds_read_b128 v[242:245], v161 offset:39936
	global_load_lds_dwordx4 v130, s[26:27]
	v_lshl_add_u64 v[250:251], s[26:27], 0, v[134:135]
	s_mov_b32 m0, s45
	s_nop 0
	global_load_lds_dwordx4 v[250:251], off
	s_waitcnt vmcnt(8)
	s_waitcnt lgkmcnt(0)
	s_barrier
	s_setprio 1
	s_waitcnt lgkmcnt(0)
	v_mfma_f32_16x16x32_bf16 v[126:129], v[152:155], v[214:217], v[126:129]
	v_mfma_f32_16x16x32_bf16 v[122:125], v[170:173], v[214:217], v[122:125]
	v_mfma_f32_16x16x32_bf16 v[110:113], v[152:155], v[222:225], v[110:113]
	v_mfma_f32_16x16x32_bf16 v[106:109], v[170:173], v[222:225], v[106:109]
	v_mfma_f32_16x16x32_bf16 v[94:97], v[152:155], v[230:233], v[94:97]
	v_mfma_f32_16x16x32_bf16 v[90:93], v[170:173], v[230:233], v[90:93]
	v_mfma_f32_16x16x32_bf16 v[78:81], v[152:155], v[238:241], v[78:81]
	v_mfma_f32_16x16x32_bf16 v[74:77], v[170:173], v[238:241], v[74:77]
	v_mfma_f32_16x16x32_bf16 v[126:129], v[166:169], v[218:221], v[126:129]
	v_mfma_f32_16x16x32_bf16 v[122:125], v[174:177], v[218:221], v[122:125]
	v_mfma_f32_16x16x32_bf16 v[110:113], v[166:169], v[226:229], v[110:113]
	v_mfma_f32_16x16x32_bf16 v[106:109], v[174:177], v[226:229], v[106:109]
	v_mfma_f32_16x16x32_bf16 v[94:97], v[166:169], v[234:237], v[94:97]
	v_mfma_f32_16x16x32_bf16 v[90:93], v[174:177], v[234:237], v[90:93]
	v_mfma_f32_16x16x32_bf16 v[78:81], v[166:169], v[242:245], v[78:81]
	v_mfma_f32_16x16x32_bf16 v[74:77], v[174:177], v[242:245], v[74:77]
	s_setprio 0
	s_setprio 1
	v_mfma_f32_16x16x32_bf16 v[118:121], v[198:201], v[214:217], v[118:121]
	v_mfma_f32_16x16x32_bf16 v[114:117], v[206:209], v[214:217], v[114:117]
	v_mfma_f32_16x16x32_bf16 v[102:105], v[198:201], v[222:225], v[102:105]
	v_mfma_f32_16x16x32_bf16 v[98:101], v[206:209], v[222:225], v[98:101]
	v_mfma_f32_16x16x32_bf16 v[86:89], v[198:201], v[230:233], v[86:89]
	v_mfma_f32_16x16x32_bf16 v[82:85], v[206:209], v[230:233], v[82:85]
	v_mfma_f32_16x16x32_bf16 v[70:73], v[198:201], v[238:241], v[70:73]
	v_mfma_f32_16x16x32_bf16 v[66:69], v[206:209], v[238:241], v[66:69]
	v_mfma_f32_16x16x32_bf16 v[118:121], v[202:205], v[218:221], v[118:121]
	v_mfma_f32_16x16x32_bf16 v[114:117], v[210:213], v[218:221], v[114:117]
	v_mfma_f32_16x16x32_bf16 v[102:105], v[202:205], v[226:229], v[102:105]
	v_mfma_f32_16x16x32_bf16 v[98:101], v[210:213], v[226:229], v[98:101]
	v_mfma_f32_16x16x32_bf16 v[86:89], v[202:205], v[234:237], v[86:89]
	v_mfma_f32_16x16x32_bf16 v[82:85], v[210:213], v[234:237], v[82:85]
	v_mfma_f32_16x16x32_bf16 v[70:73], v[202:205], v[242:245], v[70:73]
	v_mfma_f32_16x16x32_bf16 v[66:69], v[210:213], v[242:245], v[66:69]
	s_setprio 0
	s_barrier
	s_add_i32 s26, s31, s41
	v_lshl_add_u64 v[156:157], v[156:157], 0, s[88:89]
	s_mov_b32 m0, s26
	ds_read_b128 v[214:217], v161 offset:49152
	ds_read_b128 v[218:221], v161 offset:50176
	ds_read_b128 v[222:225], v161 offset:51200
	ds_read_b128 v[226:229], v161 offset:52224
	ds_read_b128 v[230:233], v161 offset:53248
	ds_read_b128 v[234:237], v161 offset:54272
	ds_read_b128 v[238:241], v161 offset:55296
	ds_read_b128 v[242:245], v161 offset:56320
	global_load_lds_dwordx4 v[156:157], off
	s_add_i32 m0, s26, 0x2000
	s_add_u32 s24, s24, 0x40080
	v_lshl_add_u64 v[156:157], v[178:179], 0, s[88:89]
	s_addc_u32 s25, s25, 0
	s_add_i32 s26, s34, s41
	global_load_lds_dwordx4 v[156:157], off
	s_mov_b32 m0, s26
	s_nop 0
	global_load_lds_dwordx4 v132, s[24:25]
	s_add_i32 m0, s26, 0x2000
	s_nop 0
	global_load_lds_dwordx4 v136, s[24:25]
	v_lshl_add_u64 v[156:157], v[246:247], 0, s[88:89]
	s_mov_b32 m0, s47
	s_nop 0
	global_load_lds_dwordx4 v[156:157], off
	v_lshl_add_u64 v[156:157], v[248:249], 0, s[88:89]
	s_mov_b32 m0, s48
	s_nop 0
	global_load_lds_dwordx4 v[156:157], off
	s_waitcnt vmcnt(8)
	s_waitcnt lgkmcnt(0)
	s_barrier
	s_setprio 1
	s_waitcnt lgkmcnt(0)
	v_mfma_f32_16x16x32_bf16 v[62:65], v[152:155], v[214:217], v[62:65]
	v_mfma_f32_16x16x32_bf16 v[58:61], v[170:173], v[214:217], v[58:61]
	v_mfma_f32_16x16x32_bf16 v[46:49], v[152:155], v[222:225], v[46:49]
	v_mfma_f32_16x16x32_bf16 v[42:45], v[170:173], v[222:225], v[42:45]
	v_mfma_f32_16x16x32_bf16 v[30:33], v[152:155], v[230:233], v[30:33]
	v_mfma_f32_16x16x32_bf16 v[26:29], v[170:173], v[230:233], v[26:29]
	v_mfma_f32_16x16x32_bf16 v[14:17], v[152:155], v[238:241], v[14:17]
	v_mfma_f32_16x16x32_bf16 v[10:13], v[170:173], v[238:241], v[10:13]
	v_mfma_f32_16x16x32_bf16 v[62:65], v[166:169], v[218:221], v[62:65]
	v_mfma_f32_16x16x32_bf16 v[58:61], v[174:177], v[218:221], v[58:61]
	v_mfma_f32_16x16x32_bf16 v[46:49], v[166:169], v[226:229], v[46:49]
	v_mfma_f32_16x16x32_bf16 v[42:45], v[174:177], v[226:229], v[42:45]
	v_mfma_f32_16x16x32_bf16 v[30:33], v[166:169], v[234:237], v[30:33]
	v_mfma_f32_16x16x32_bf16 v[26:29], v[174:177], v[234:237], v[26:29]
	v_mfma_f32_16x16x32_bf16 v[14:17], v[166:169], v[242:245], v[14:17]
	v_mfma_f32_16x16x32_bf16 v[10:13], v[174:177], v[242:245], v[10:13]
	s_setprio 0
	s_setprio 1
	v_mfma_f32_16x16x32_bf16 v[54:57], v[198:201], v[214:217], v[54:57]
	v_mfma_f32_16x16x32_bf16 v[50:53], v[206:209], v[214:217], v[50:53]
	v_mfma_f32_16x16x32_bf16 v[38:41], v[198:201], v[222:225], v[38:41]
	v_mfma_f32_16x16x32_bf16 v[34:37], v[206:209], v[222:225], v[34:37]
	v_mfma_f32_16x16x32_bf16 v[22:25], v[198:201], v[230:233], v[22:25]
	v_mfma_f32_16x16x32_bf16 v[18:21], v[206:209], v[230:233], v[18:21]
	v_mfma_f32_16x16x32_bf16 v[6:9], v[198:201], v[238:241], v[6:9]
	v_mfma_f32_16x16x32_bf16 v[2:5], v[206:209], v[238:241], v[2:5]
	v_mfma_f32_16x16x32_bf16 v[54:57], v[202:205], v[218:221], v[54:57]
	v_mfma_f32_16x16x32_bf16 v[50:53], v[210:213], v[218:221], v[50:53]
	v_mfma_f32_16x16x32_bf16 v[38:41], v[202:205], v[226:229], v[38:41]
	v_mfma_f32_16x16x32_bf16 v[34:37], v[210:213], v[226:229], v[34:37]
	v_mfma_f32_16x16x32_bf16 v[22:25], v[202:205], v[234:237], v[22:25]
	v_mfma_f32_16x16x32_bf16 v[18:21], v[210:213], v[234:237], v[18:21]
	v_mfma_f32_16x16x32_bf16 v[6:9], v[202:205], v[242:245], v[6:9]
	v_mfma_f32_16x16x32_bf16 v[2:5], v[210:213], v[242:245], v[2:5]
	s_setprio 0
	s_barrier
	s_add_i32 s30, s30, 2
	s_add_u32 s10, s10, 0x100
	s_addc_u32 s11, s11, 0
	s_add_u32 s28, s28, 0x100
	s_addc_u32 s29, s29, 0
	s_cmp_gt_u32 s30, 13
	s_cbranch_scc0 .LBB0_397
	s_and_b64 vcc, exec, s[14:15]
	s_cbranch_vccz .LBB0_400
	s_barrier

.LBB0_1069:
	s_add_u32 s2, s6, 0xde00000
	s_addc_u32 s3, s7, 0
	s_lshl_b32 s8, s8, 5
	s_and_b32 s12, s8, 0x60
	s_add_i32 m0, s46, 0x18000
	v_lshl_add_u64 v[8:9], v[8:9], 0, s[88:89]
	s_lshl_b32 s11, s5, 13
	s_lshl_b32 s13, s12, 7
	s_waitcnt vmcnt(2)
	s_barrier
	global_load_lds_dwordx4 v[8:9], off
	v_lshl_add_u64 v[6:7], v[6:7], 0, s[88:89]
	s_add_i32 m0, s46, 0x1a000
	s_add_i32 s50, s46, 0x8000
	s_add_i32 s51, s46, 0xa000
	global_load_lds_dwordx4 v[6:7], off
	v_lshl_add_u64 v[2:3], v[2:3], 0, s[88:89]
	s_mov_b32 m0, s50
	s_add_u32 s8, s22, 0x40080
	global_load_lds_dwordx4 v[2:3], off
	v_lshl_add_u64 v[2:3], v[4:5], 0, s[88:89]
	s_mov_b32 m0, s51
	s_addc_u32 s9, s23, 0
	global_load_lds_dwordx4 v[2:3], off
	s_add_i32 m0, s46, 0x1c000
	s_nop 0
	global_load_lds_dwordx4 v132, s[8:9]
	v_lshl_add_u64 v[2:3], s[8:9], 0, v[134:135]
	s_add_i32 m0, s46, 0x1e000
	s_sext_i32_i8 s21, s4
	global_load_lds_dwordx4 v[2:3], off
	v_bfe_u32 v3, v0, 4, 2
	v_and_b32_e32 v2, 15, v0
	v_lshlrev_b32_e32 v4, 4, v3
	v_lshlrev_b32_e32 v0, 2, v0
	v_lshl_or_b32 v137, s5, 6, v2
	v_lshl_or_b32 v2, v2, 6, v4
	v_and_b32_e32 v0, 32, v0
	v_bitop3_b32 v4, v2, s11, v0 bitop3:0xde
	s_waitcnt vmcnt(0)
	v_bitop3_b32 v148, v2, s13, v0 bitop3:0xde
	v_lshlrev_b32_e32 v0, 14, v10
	v_and_b32_e32 v0, 0xffff8000, v0
	v_lshl_add_u32 v0, v11, 11, v0
	v_and_b32_e32 v2, 1, v10
	s_add_u32 s4, s6, 0x2401600
	v_lshl_or_b32 v0, v2, 6, v0
	s_addc_u32 s5, s7, 0
	v_lshl_add_u32 v138, v12, 1, v0
	v_lshlrev_b32_e32 v0, 14, v13
	s_add_u32 s8, s6, 0x2401e00
	v_and_b32_e32 v0, 0xffff8000, v0
	s_waitcnt vmcnt(6)
	s_addc_u32 s9, s7, 0
	v_lshl_add_u32 v0, v14, 11, v0
	v_and_b32_e32 v2, 1, v13
	s_cmpk_lt_u32 s10, 0x100
	v_lshl_or_b32 v0, v2, 6, v0
	v_lshl_or_b32 v136, v3, 2, s12
	v_add_u32_e32 v149, 0xb0, v137
	s_cselect_b64 s[10:11], -1, 0
	s_ashr_i32 s52, s38, 31
	v_mov_b32_e32 v139, v1
	v_lshl_add_u32 v140, v15, 1, v0
	v_mov_b32_e32 v141, v1
	s_mov_b32 s53, 0
	v_add_u32_e32 v150, 0, v4
	s_barrier
	s_branch .LBB0_1072

.LBB0_1084:
	s_add_i32 s59, s59, 2
	s_add_u32 s34, s30, s80
	s_addc_u32 s35, s31, 0
	s_add_u32 s61, s28, s80
	s_addc_u32 s62, s29, 0
	s_add_i32 s63, 0, 0x10000
	s_cmp_eq_u32 s80, s26
	s_cselect_b32 s37, s15, s35
	s_cselect_b32 s36, s33, s34
	v_add_u32_e32 v0, s63, v148
	s_cselect_b32 s35, s54, s62
	s_cselect_b32 s34, s55, s61
	s_add_i32 s61, 0, 0x14000
	ds_read_b128 v[166:169], v0
	ds_read_b128 v[170:173], v0 offset:1024
	ds_read_b128 v[174:177], v0 offset:2048
	ds_read_b128 v[198:201], v0 offset:3072
	v_add_u32_e32 v0, s61, v148
	ds_read_b128 v[202:205], v0
	ds_read_b128 v[206:209], v0 offset:1024
	ds_read_b128 v[210:213], v0 offset:2048
	ds_read_b128 v[214:217], v0 offset:3072
	v_lshl_add_u64 v[178:179], v[146:147], 0, s[80:81]
	s_add_i32 m0, s46, 0xc000
	ds_read_b128 v[218:221], v150
	ds_read_b128 v[222:225], v150 offset:1024
	ds_read_b128 v[226:229], v150 offset:2048
	ds_read_b128 v[230:233], v150 offset:3072
	ds_read_b128 v[234:237], v150 offset:4096
	ds_read_b128 v[238:241], v150 offset:5120
	ds_read_b128 v[242:245], v150 offset:6144
	ds_read_b128 v[246:249], v150 offset:7168
	global_load_lds_dwordx4 v[178:179], off
	v_lshl_add_u64 v[178:179], v[2:3], 0, s[80:81]
	s_add_i32 m0, s46, 0xe000
	s_nop 0
	global_load_lds_dwordx4 v[178:179], off
	s_waitcnt vmcnt(8)
	s_waitcnt lgkmcnt(0)
	s_barrier
	s_setprio 1
	s_waitcnt lgkmcnt(0)
	v_mfma_f32_16x16x32_bf16 v[128:131], v[166:169], v[218:221], v[128:131]
	v_mfma_f32_16x16x32_bf16 v[124:127], v[174:177], v[218:221], v[124:127]
	v_mfma_f32_16x16x32_bf16 v[112:115], v[166:169], v[226:229], v[112:115]
	v_mfma_f32_16x16x32_bf16 v[108:111], v[174:177], v[226:229], v[108:111]
	v_mfma_f32_16x16x32_bf16 v[96:99], v[166:169], v[234:237], v[96:99]
	v_mfma_f32_16x16x32_bf16 v[92:95], v[174:177], v[234:237], v[92:95]
	v_mfma_f32_16x16x32_bf16 v[80:83], v[166:169], v[242:245], v[80:83]
	v_mfma_f32_16x16x32_bf16 v[76:79], v[174:177], v[242:245], v[76:79]
	v_mfma_f32_16x16x32_bf16 v[128:131], v[170:173], v[222:225], v[128:131]
	v_mfma_f32_16x16x32_bf16 v[124:127], v[198:201], v[222:225], v[124:127]
	v_mfma_f32_16x16x32_bf16 v[112:115], v[170:173], v[230:233], v[112:115]
	v_mfma_f32_16x16x32_bf16 v[108:111], v[198:201], v[230:233], v[108:111]
	v_mfma_f32_16x16x32_bf16 v[96:99], v[170:173], v[238:241], v[96:99]
	v_mfma_f32_16x16x32_bf16 v[92:95], v[198:201], v[238:241], v[92:95]
	v_mfma_f32_16x16x32_bf16 v[80:83], v[170:173], v[246:249], v[80:83]
	v_mfma_f32_16x16x32_bf16 v[76:79], v[198:201], v[246:249], v[76:79]
	s_setprio 0
	s_setprio 1
	v_mfma_f32_16x16x32_bf16 v[120:123], v[202:205], v[218:221], v[120:123]
	v_mfma_f32_16x16x32_bf16 v[116:119], v[210:213], v[218:221], v[116:119]
	v_mfma_f32_16x16x32_bf16 v[104:107], v[202:205], v[226:229], v[104:107]
	v_mfma_f32_16x16x32_bf16 v[100:103], v[210:213], v[226:229], v[100:103]
	v_mfma_f32_16x16x32_bf16 v[88:91], v[202:205], v[234:237], v[88:91]
	v_mfma_f32_16x16x32_bf16 v[84:87], v[210:213], v[234:237], v[84:87]
	v_mfma_f32_16x16x32_bf16 v[72:75], v[202:205], v[242:245], v[72:75]
	v_mfma_f32_16x16x32_bf16 v[68:71], v[210:213], v[242:245], v[68:71]
	v_mfma_f32_16x16x32_bf16 v[120:123], v[206:209], v[222:225], v[120:123]
	v_mfma_f32_16x16x32_bf16 v[116:119], v[214:217], v[222:225], v[116:119]
	v_mfma_f32_16x16x32_bf16 v[104:107], v[206:209], v[230:233], v[104:107]
	v_mfma_f32_16x16x32_bf16 v[100:103], v[214:217], v[230:233], v[100:103]
	v_mfma_f32_16x16x32_bf16 v[88:91], v[206:209], v[238:241], v[88:91]
	v_mfma_f32_16x16x32_bf16 v[84:87], v[214:217], v[238:241], v[84:87]
	v_mfma_f32_16x16x32_bf16 v[72:75], v[206:209], v[246:249], v[72:75]
	v_mfma_f32_16x16x32_bf16 v[68:71], v[214:217], v[246:249], v[68:71]
	s_setprio 0
	s_barrier
	s_add_i32 s62, s63, s45
	v_lshl_add_u64 v[178:179], s[34:35], 0, v[132:133]
	s_mov_b32 m0, s62
	ds_read_b128 v[218:221], v150 offset:16384
	ds_read_b128 v[222:225], v150 offset:17408
	ds_read_b128 v[226:229], v150 offset:18432
	ds_read_b128 v[230:233], v150 offset:19456
	ds_read_b128 v[234:237], v150 offset:20480
	ds_read_b128 v[238:241], v150 offset:21504
	ds_read_b128 v[242:245], v150 offset:22528
	ds_read_b128 v[246:249], v150 offset:23552
	global_load_lds_dwordx4 v[178:179], off
	s_add_i32 m0, s62, 0x2000
	s_add_u32 s62, s34, 0x40000
	v_lshl_add_u64 v[250:251], s[34:35], 0, v[134:135]
	s_addc_u32 s63, s35, 0
	s_add_i32 s61, s61, s45
	global_load_lds_dwordx4 v[250:251], off
	s_mov_b32 m0, s61
	v_lshl_add_u64 v[162:163], s[36:37], 0, v[134:135]
	global_load_lds_dwordx4 v132, s[62:63]
	s_add_i32 m0, s61, 0x2000
	s_nop 0
	global_load_lds_dwordx4 v134, s[62:63]
	v_lshl_add_u64 v[252:253], s[36:37], 0, v[132:133]
	s_mov_b32 m0, s46
	s_nop 0
	global_load_lds_dwordx4 v[252:253], off
	s_mov_b32 m0, s47
	s_nop 0
	global_load_lds_dwordx4 v[162:163], off
	s_waitcnt vmcnt(8)
	s_waitcnt lgkmcnt(0)
	s_barrier
	s_setprio 1
	s_waitcnt lgkmcnt(0)
	v_mfma_f32_16x16x32_bf16 v[64:67], v[166:169], v[218:221], v[64:67]
	v_mfma_f32_16x16x32_bf16 v[60:63], v[174:177], v[218:221], v[60:63]
	v_mfma_f32_16x16x32_bf16 v[48:51], v[166:169], v[226:229], v[48:51]
	v_mfma_f32_16x16x32_bf16 v[44:47], v[174:177], v[226:229], v[44:47]
	v_mfma_f32_16x16x32_bf16 v[32:35], v[166:169], v[234:237], v[32:35]
	v_mfma_f32_16x16x32_bf16 v[28:31], v[174:177], v[234:237], v[28:31]
	v_mfma_f32_16x16x32_bf16 v[16:19], v[166:169], v[242:245], v[16:19]
	v_mfma_f32_16x16x32_bf16 v[12:15], v[174:177], v[242:245], v[12:15]
	v_mfma_f32_16x16x32_bf16 v[64:67], v[170:173], v[222:225], v[64:67]
	v_mfma_f32_16x16x32_bf16 v[60:63], v[198:201], v[222:225], v[60:63]
	v_mfma_f32_16x16x32_bf16 v[48:51], v[170:173], v[230:233], v[48:51]
	v_mfma_f32_16x16x32_bf16 v[44:47], v[198:201], v[230:233], v[44:47]
	v_mfma_f32_16x16x32_bf16 v[32:35], v[170:173], v[238:241], v[32:35]
	v_mfma_f32_16x16x32_bf16 v[28:31], v[198:201], v[238:241], v[28:31]
	v_mfma_f32_16x16x32_bf16 v[16:19], v[170:173], v[246:249], v[16:19]
	v_mfma_f32_16x16x32_bf16 v[12:15], v[198:201], v[246:249], v[12:15]
	s_setprio 0
	s_setprio 1
	v_mfma_f32_16x16x32_bf16 v[56:59], v[202:205], v[218:221], v[56:59]
	v_mfma_f32_16x16x32_bf16 v[52:55], v[210:213], v[218:221], v[52:55]
	v_mfma_f32_16x16x32_bf16 v[40:43], v[202:205], v[226:229], v[40:43]
	v_mfma_f32_16x16x32_bf16 v[36:39], v[210:213], v[226:229], v[36:39]
	v_mfma_f32_16x16x32_bf16 v[24:27], v[202:205], v[234:237], v[24:27]
	v_mfma_f32_16x16x32_bf16 v[20:23], v[210:213], v[234:237], v[20:23]
	v_mfma_f32_16x16x32_bf16 v[8:11], v[202:205], v[242:245], v[8:11]
	v_mfma_f32_16x16x32_bf16 v[4:7], v[210:213], v[242:245], v[4:7]
	v_mfma_f32_16x16x32_bf16 v[56:59], v[206:209], v[222:225], v[56:59]
	v_mfma_f32_16x16x32_bf16 v[52:55], v[214:217], v[222:225], v[52:55]
	v_mfma_f32_16x16x32_bf16 v[40:43], v[206:209], v[230:233], v[40:43]
	v_mfma_f32_16x16x32_bf16 v[36:39], v[214:217], v[230:233], v[36:39]
	v_mfma_f32_16x16x32_bf16 v[24:27], v[206:209], v[238:241], v[24:27]
	v_mfma_f32_16x16x32_bf16 v[20:23], v[214:217], v[238:241], v[20:23]
	v_mfma_f32_16x16x32_bf16 v[8:11], v[206:209], v[246:249], v[8:11]
	v_mfma_f32_16x16x32_bf16 v[4:7], v[214:217], v[246:249], v[4:7]
	s_setprio 0
	s_barrier
	s_add_i32 s61, 0, 0x18000
	v_add_u32_e32 v0, s61, v148
	s_add_i32 s62, 0, 0x1c000
	ds_read_b128 v[166:169], v0
	ds_read_b128 v[170:173], v0 offset:1024
	ds_read_b128 v[174:177], v0 offset:2048
	ds_read_b128 v[198:201], v0 offset:3072
	v_add_u32_e32 v0, s62, v148
	ds_read_b128 v[202:205], v0
	ds_read_b128 v[206:209], v0 offset:1024
	ds_read_b128 v[210:213], v0 offset:2048
	ds_read_b128 v[214:217], v0 offset:3072
	s_add_u32 s36, s36, 0x40000
	s_addc_u32 s37, s37, 0
	s_mov_b32 m0, s48
	ds_read_b128 v[218:221], v150 offset:32768
	ds_read_b128 v[222:225], v150 offset:33792
	ds_read_b128 v[226:229], v150 offset:34816
	ds_read_b128 v[230:233], v150 offset:35840
	ds_read_b128 v[234:237], v150 offset:36864
	ds_read_b128 v[238:241], v150 offset:37888
	ds_read_b128 v[242:245], v150 offset:38912
	ds_read_b128 v[246:249], v150 offset:39936
	global_load_lds_dwordx4 v132, s[36:37]
	s_mov_b32 m0, s49
	s_nop 0
	global_load_lds_dwordx4 v134, s[36:37]
	s_waitcnt vmcnt(8)
	s_waitcnt lgkmcnt(0)
	s_barrier
	s_setprio 1
	s_waitcnt lgkmcnt(0)
	v_mfma_f32_16x16x32_bf16 v[128:131], v[166:169], v[218:221], v[128:131]
	v_mfma_f32_16x16x32_bf16 v[124:127], v[174:177], v[218:221], v[124:127]
	v_mfma_f32_16x16x32_bf16 v[112:115], v[166:169], v[226:229], v[112:115]
	v_mfma_f32_16x16x32_bf16 v[108:111], v[174:177], v[226:229], v[108:111]
	v_mfma_f32_16x16x32_bf16 v[96:99], v[166:169], v[234:237], v[96:99]
	v_mfma_f32_16x16x32_bf16 v[92:95], v[174:177], v[234:237], v[92:95]
	v_mfma_f32_16x16x32_bf16 v[80:83], v[166:169], v[242:245], v[80:83]
	v_mfma_f32_16x16x32_bf16 v[76:79], v[174:177], v[242:245], v[76:79]
	v_mfma_f32_16x16x32_bf16 v[128:131], v[170:173], v[222:225], v[128:131]
	v_mfma_f32_16x16x32_bf16 v[124:127], v[198:201], v[222:225], v[124:127]
	v_mfma_f32_16x16x32_bf16 v[112:115], v[170:173], v[230:233], v[112:115]
	v_mfma_f32_16x16x32_bf16 v[108:111], v[198:201], v[230:233], v[108:111]
	v_mfma_f32_16x16x32_bf16 v[96:99], v[170:173], v[238:241], v[96:99]
	v_mfma_f32_16x16x32_bf16 v[92:95], v[198:201], v[238:241], v[92:95]
	v_mfma_f32_16x16x32_bf16 v[80:83], v[170:173], v[246:249], v[80:83]
	v_mfma_f32_16x16x32_bf16 v[76:79], v[198:201], v[246:249], v[76:79]
	s_setprio 0
	s_setprio 1
	v_mfma_f32_16x16x32_bf16 v[120:123], v[202:205], v[218:221], v[120:123]
	v_mfma_f32_16x16x32_bf16 v[116:119], v[210:213], v[218:221], v[116:119]
	v_mfma_f32_16x16x32_bf16 v[104:107], v[202:205], v[226:229], v[104:107]
	v_mfma_f32_16x16x32_bf16 v[100:103], v[210:213], v[226:229], v[100:103]
	v_mfma_f32_16x16x32_bf16 v[88:91], v[202:205], v[234:237], v[88:91]
	v_mfma_f32_16x16x32_bf16 v[84:87], v[210:213], v[234:237], v[84:87]
	v_mfma_f32_16x16x32_bf16 v[72:75], v[202:205], v[242:245], v[72:75]
	v_mfma_f32_16x16x32_bf16 v[68:71], v[210:213], v[242:245], v[68:71]
	v_mfma_f32_16x16x32_bf16 v[120:123], v[206:209], v[222:225], v[120:123]
	v_mfma_f32_16x16x32_bf16 v[116:119], v[214:217], v[222:225], v[116:119]
	v_mfma_f32_16x16x32_bf16 v[104:107], v[206:209], v[230:233], v[104:107]
	v_mfma_f32_16x16x32_bf16 v[100:103], v[214:217], v[230:233], v[100:103]
	v_mfma_f32_16x16x32_bf16 v[88:91], v[206:209], v[238:241], v[88:91]
	v_mfma_f32_16x16x32_bf16 v[84:87], v[214:217], v[238:241], v[84:87]
	v_mfma_f32_16x16x32_bf16 v[72:75], v[206:209], v[246:249], v[72:75]
	v_mfma_f32_16x16x32_bf16 v[68:71], v[214:217], v[246:249], v[68:71]
	s_setprio 0
	s_barrier
	s_add_i32 s36, s61, s45
	v_lshl_add_u64 v[164:165], v[178:179], 0, s[88:89]
	s_mov_b32 m0, s36
	ds_read_b128 v[218:221], v150 offset:49152
	ds_read_b128 v[222:225], v150 offset:50176
	ds_read_b128 v[226:229], v150 offset:51200
	ds_read_b128 v[230:233], v150 offset:52224
	ds_read_b128 v[234:237], v150 offset:53248
	ds_read_b128 v[238:241], v150 offset:54272
	ds_read_b128 v[242:245], v150 offset:55296
	ds_read_b128 v[246:249], v150 offset:56320
	global_load_lds_dwordx4 v[164:165], off
	s_add_i32 m0, s36, 0x2000
	s_add_u32 s34, s34, 0x40080
	v_lshl_add_u64 v[164:165], v[250:251], 0, s[88:89]
	s_addc_u32 s35, s35, 0
	s_add_i32 s36, s62, s45
	global_load_lds_dwordx4 v[164:165], off
	s_mov_b32 m0, s36
	v_lshl_add_u64 v[162:163], v[162:163], 0, s[88:89]
	global_load_lds_dwordx4 v132, s[34:35]
	s_add_i32 m0, s36, 0x2000
	s_nop 0
	global_load_lds_dwordx4 v134, s[34:35]
	v_lshl_add_u64 v[164:165], v[252:253], 0, s[88:89]
	s_mov_b32 m0, s50
	s_nop 0
	global_load_lds_dwordx4 v[164:165], off
	s_mov_b32 m0, s51
	s_nop 0
	global_load_lds_dwordx4 v[162:163], off
	s_waitcnt vmcnt(8)
	s_waitcnt lgkmcnt(0)
	s_barrier
	s_setprio 1
	s_waitcnt lgkmcnt(0)
	v_mfma_f32_16x16x32_bf16 v[64:67], v[166:169], v[218:221], v[64:67]
	v_mfma_f32_16x16x32_bf16 v[60:63], v[174:177], v[218:221], v[60:63]
	v_mfma_f32_16x16x32_bf16 v[48:51], v[166:169], v[226:229], v[48:51]
	v_mfma_f32_16x16x32_bf16 v[44:47], v[174:177], v[226:229], v[44:47]
	v_mfma_f32_16x16x32_bf16 v[32:35], v[166:169], v[234:237], v[32:35]
	v_mfma_f32_16x16x32_bf16 v[28:31], v[174:177], v[234:237], v[28:31]
	v_mfma_f32_16x16x32_bf16 v[16:19], v[166:169], v[242:245], v[16:19]
	v_mfma_f32_16x16x32_bf16 v[12:15], v[174:177], v[242:245], v[12:15]
	v_mfma_f32_16x16x32_bf16 v[64:67], v[170:173], v[222:225], v[64:67]
	v_mfma_f32_16x16x32_bf16 v[60:63], v[198:201], v[222:225], v[60:63]
	v_mfma_f32_16x16x32_bf16 v[48:51], v[170:173], v[230:233], v[48:51]
	v_mfma_f32_16x16x32_bf16 v[44:47], v[198:201], v[230:233], v[44:47]
	v_mfma_f32_16x16x32_bf16 v[32:35], v[170:173], v[238:241], v[32:35]
	v_mfma_f32_16x16x32_bf16 v[28:31], v[198:201], v[238:241], v[28:31]
	v_mfma_f32_16x16x32_bf16 v[16:19], v[170:173], v[246:249], v[16:19]
	v_mfma_f32_16x16x32_bf16 v[12:15], v[198:201], v[246:249], v[12:15]
	s_setprio 0
	s_setprio 1
	v_mfma_f32_16x16x32_bf16 v[56:59], v[202:205], v[218:221], v[56:59]
	v_mfma_f32_16x16x32_bf16 v[52:55], v[210:213], v[218:221], v[52:55]
	v_mfma_f32_16x16x32_bf16 v[40:43], v[202:205], v[226:229], v[40:43]
	v_mfma_f32_16x16x32_bf16 v[36:39], v[210:213], v[226:229], v[36:39]
	v_mfma_f32_16x16x32_bf16 v[24:27], v[202:205], v[234:237], v[24:27]
	v_mfma_f32_16x16x32_bf16 v[20:23], v[210:213], v[234:237], v[20:23]
	v_mfma_f32_16x16x32_bf16 v[8:11], v[202:205], v[242:245], v[8:11]
	v_mfma_f32_16x16x32_bf16 v[4:7], v[210:213], v[242:245], v[4:7]
	v_mfma_f32_16x16x32_bf16 v[56:59], v[206:209], v[222:225], v[56:59]
	v_mfma_f32_16x16x32_bf16 v[52:55], v[214:217], v[222:225], v[52:55]
	v_mfma_f32_16x16x32_bf16 v[40:43], v[206:209], v[230:233], v[40:43]
	v_mfma_f32_16x16x32_bf16 v[36:39], v[214:217], v[230:233], v[36:39]
	v_mfma_f32_16x16x32_bf16 v[24:27], v[206:209], v[238:241], v[24:27]
	v_mfma_f32_16x16x32_bf16 v[20:23], v[214:217], v[238:241], v[20:23]
	v_mfma_f32_16x16x32_bf16 v[8:11], v[206:209], v[246:249], v[8:11]
	v_mfma_f32_16x16x32_bf16 v[4:7], v[214:217], v[246:249], v[4:7]
	s_setprio 0
	s_barrier
	s_add_u32 s30, s30, 0x100
	s_addc_u32 s31, s31, 0
	s_add_u32 s28, s28, 0x100
	s_addc_u32 s29, s29, 0
	s_add_u32 s26, s26, 0xffffff00
	s_addc_u32 s27, s27, -1
	v_lshl_add_u64 v[146:147], v[146:147], 0, s[70:71]
	s_cmp_ge_u32 s59, s60
	v_lshl_add_u64 v[2:3], v[2:3], 0, s[70:71]
	s_cbranch_scc0 .LBB0_1084
	s_branch .LBB0_1079

.LBB0_1144:
	s_add_u32 s12, s2, 0xbe00000
	s_addc_u32 s13, s3, 0
	s_and_b32 s48, s6, 3
	s_add_i32 m0, s44, 0x18000
	v_lshl_add_u64 v[8:9], v[8:9], 0, s[88:89]
	s_lshl_b32 s6, s7, 13
	s_lshl_b32 s15, s48, 12
	s_waitcnt vmcnt(2)
	s_barrier
	global_load_lds_dwordx4 v[8:9], off
	v_lshl_add_u64 v[6:7], v[6:7], 0, s[88:89]
	s_add_i32 m0, s44, 0x1a000
	s_add_i32 s49, s44, 0x8000
	s_add_i32 s50, s44, 0xa000
	global_load_lds_dwordx4 v[6:7], off
	v_lshl_add_u64 v[2:3], v[2:3], 0, s[88:89]
	s_mov_b32 m0, s49
	s_add_u32 s8, s30, 0x40080
	global_load_lds_dwordx4 v[2:3], off
	v_lshl_add_u64 v[2:3], v[4:5], 0, s[88:89]
	s_mov_b32 m0, s50
	s_addc_u32 s9, s31, 0
	global_load_lds_dwordx4 v[2:3], off
	s_add_i32 m0, s44, 0x1c000
	s_nop 0
	global_load_lds_dwordx4 v0, s[8:9]
	v_lshl_add_u64 v[2:3], s[8:9], 0, v[130:131]
	s_add_i32 m0, s44, 0x1e000
	s_mov_b64 s[8:9], 0x40080
	global_load_lds_dwordx4 v[2:3], off
	v_bfe_u32 v2, v10, 4, 2
	v_and_b32_e32 v3, 15, v10
	v_lshlrev_b32_e32 v4, 4, v2
	s_waitcnt vmcnt(0)
	v_lshl_or_b32 v148, s7, 6, v3
	v_lshl_or_b32 v3, v3, 6, v4
	v_lshlrev_b32_e32 v4, 2, v10
	v_and_b32_e32 v4, 32, v4
	v_bitop3_b32 v5, v3, s6, v4 bitop3:0xde
	v_bitop3_b32 v149, v3, s15, v4 bitop3:0xde
	v_lshlrev_b32_e32 v3, 2, v2
	v_cmp_eq_u32_e64 s[6:7], 0, v2
	v_lshlrev_b32_e32 v2, 13, v11
	v_and_b32_e32 v2, 0x7fffc000, v2
	v_lshl_add_u32 v2, v12, 10, v2
	v_or_b32_e32 v2, v2, v13
	v_lshl_or_b32 v150, s48, 5, v3
	v_add_lshl_u32 v2, v2, v14, 1
	v_mov_b32_e32 v3, v1
	v_lshl_add_u64 v[132:133], v[2:3], 0, s[8:9]
	v_lshlrev_b32_e32 v2, 13, v15
	v_and_b32_e32 v2, 0x7fffc000, v2
	v_lshl_add_u32 v2, v16, 10, v2
	s_waitcnt vmcnt(6)
	v_or_b32_e32 v2, v2, v17
	s_cmpk_lt_u32 s14, 0x100
	v_add_lshl_u32 v2, v2, v18, 1
	s_cselect_b64 s[14:15], -1, 0
	s_mov_b32 s51, 0
	s_ashr_i32 s52, s33, 31
	s_ashr_i32 s53, s38, 31
	v_lshl_add_u64 v[134:135], v[2:3], 0, s[8:9]
	v_add_u32_e32 v151, 0, v5
	s_barrier
	s_branch .LBB0_1147

.LBB0_1154:
	s_add_u32 s30, s28, 0x100
	s_addc_u32 s31, s29, 0
	s_add_i32 s57, 0, 0x10000
	s_cmp_eq_u32 s56, 12
	s_cselect_b32 s37, s19, s31
	s_cselect_b32 s36, s25, s30
	s_cselect_b32 s35, s17, s55
	s_cselect_b32 s34, s27, s54
	s_add_i32 s58, 0, 0x14000
	v_add_u32_e32 v152, s57, v149
	v_add_u32_e32 v161, s58, v149
	ds_read_b128 v[136:139], v152
	ds_read_b128 v[140:143], v152 offset:1024
	ds_read_b128 v[144:147], v152 offset:2048
	ds_read_b128 v[152:155], v152 offset:3072
	ds_read_b128 v[156:159], v161
	ds_read_b128 v[166:169], v161 offset:1024
	ds_read_b128 v[170:173], v161 offset:2048
	ds_read_b128 v[174:177], v161 offset:3072
	s_add_i32 m0, s44, 0xc000
	ds_read_b128 v[198:201], v151
	ds_read_b128 v[202:205], v151 offset:1024
	ds_read_b128 v[206:209], v151 offset:2048
	ds_read_b128 v[210:213], v151 offset:3072
	ds_read_b128 v[214:217], v151 offset:4096
	ds_read_b128 v[218:221], v151 offset:5120
	ds_read_b128 v[222:225], v151 offset:6144
	ds_read_b128 v[226:229], v151 offset:7168
	global_load_lds_dwordx4 v132, s[28:29]
	s_add_i32 m0, s44, 0xe000
	s_nop 0
	global_load_lds_dwordx4 v134, s[28:29]
	s_waitcnt vmcnt(8)
	s_waitcnt lgkmcnt(0)
	s_barrier
	s_setprio 1
	s_waitcnt lgkmcnt(0)
	v_mfma_f32_16x16x32_bf16 v[126:129], v[136:139], v[198:201], v[126:129]
	v_mfma_f32_16x16x32_bf16 v[122:125], v[144:147], v[198:201], v[122:125]
	v_mfma_f32_16x16x32_bf16 v[110:113], v[136:139], v[206:209], v[110:113]
	v_mfma_f32_16x16x32_bf16 v[106:109], v[144:147], v[206:209], v[106:109]
	v_mfma_f32_16x16x32_bf16 v[94:97], v[136:139], v[214:217], v[94:97]
	v_mfma_f32_16x16x32_bf16 v[90:93], v[144:147], v[214:217], v[90:93]
	v_mfma_f32_16x16x32_bf16 v[78:81], v[136:139], v[222:225], v[78:81]
	v_mfma_f32_16x16x32_bf16 v[74:77], v[144:147], v[222:225], v[74:77]
	v_mfma_f32_16x16x32_bf16 v[126:129], v[140:143], v[202:205], v[126:129]
	v_mfma_f32_16x16x32_bf16 v[122:125], v[152:155], v[202:205], v[122:125]
	v_mfma_f32_16x16x32_bf16 v[110:113], v[140:143], v[210:213], v[110:113]
	v_mfma_f32_16x16x32_bf16 v[106:109], v[152:155], v[210:213], v[106:109]
	v_mfma_f32_16x16x32_bf16 v[94:97], v[140:143], v[218:221], v[94:97]
	v_mfma_f32_16x16x32_bf16 v[90:93], v[152:155], v[218:221], v[90:93]
	v_mfma_f32_16x16x32_bf16 v[78:81], v[140:143], v[226:229], v[78:81]
	v_mfma_f32_16x16x32_bf16 v[74:77], v[152:155], v[226:229], v[74:77]
	s_setprio 0
	s_setprio 1
	v_mfma_f32_16x16x32_bf16 v[118:121], v[156:159], v[198:201], v[118:121]
	v_mfma_f32_16x16x32_bf16 v[114:117], v[170:173], v[198:201], v[114:117]
	v_mfma_f32_16x16x32_bf16 v[102:105], v[156:159], v[206:209], v[102:105]
	v_mfma_f32_16x16x32_bf16 v[98:101], v[170:173], v[206:209], v[98:101]
	v_mfma_f32_16x16x32_bf16 v[86:89], v[156:159], v[214:217], v[86:89]
	v_mfma_f32_16x16x32_bf16 v[82:85], v[170:173], v[214:217], v[82:85]
	v_mfma_f32_16x16x32_bf16 v[70:73], v[156:159], v[222:225], v[70:73]
	v_mfma_f32_16x16x32_bf16 v[66:69], v[170:173], v[222:225], v[66:69]
	v_mfma_f32_16x16x32_bf16 v[118:121], v[166:169], v[202:205], v[118:121]
	v_mfma_f32_16x16x32_bf16 v[114:117], v[174:177], v[202:205], v[114:117]
	v_mfma_f32_16x16x32_bf16 v[102:105], v[166:169], v[210:213], v[102:105]
	v_mfma_f32_16x16x32_bf16 v[98:101], v[174:177], v[210:213], v[98:101]
	v_mfma_f32_16x16x32_bf16 v[86:89], v[166:169], v[218:221], v[86:89]
	v_mfma_f32_16x16x32_bf16 v[82:85], v[174:177], v[218:221], v[82:85]
	v_mfma_f32_16x16x32_bf16 v[70:73], v[166:169], v[226:229], v[70:73]
	v_mfma_f32_16x16x32_bf16 v[66:69], v[174:177], v[226:229], v[66:69]
	s_setprio 0
	s_barrier
	s_add_i32 s28, s57, s43
	v_lshl_add_u64 v[162:163], s[34:35], 0, v[0:1]
	s_mov_b32 m0, s28
	ds_read_b128 v[198:201], v151 offset:16384
	ds_read_b128 v[202:205], v151 offset:17408
	ds_read_b128 v[206:209], v151 offset:18432
	ds_read_b128 v[210:213], v151 offset:19456
	ds_read_b128 v[214:217], v151 offset:20480
	ds_read_b128 v[218:221], v151 offset:21504
	ds_read_b128 v[222:225], v151 offset:22528
	ds_read_b128 v[226:229], v151 offset:23552
	global_load_lds_dwordx4 v[162:163], off
	s_add_i32 m0, s28, 0x2000
	s_add_u32 s28, s34, 0x40000
	v_lshl_add_u64 v[164:165], s[34:35], 0, v[130:131]
	s_addc_u32 s29, s35, 0
	s_add_i32 s57, s58, s43
	global_load_lds_dwordx4 v[164:165], off
	s_mov_b32 m0, s57
	v_lshl_add_u64 v[230:231], s[36:37], 0, v[130:131]
	global_load_lds_dwordx4 v0, s[28:29]
	s_add_i32 m0, s57, 0x2000
	s_nop 0
	global_load_lds_dwordx4 v130, s[28:29]
	v_lshl_add_u64 v[178:179], s[36:37], 0, v[0:1]
	s_mov_b32 m0, s44
	s_nop 0
	global_load_lds_dwordx4 v[178:179], off
	s_mov_b32 m0, s45
	s_nop 0
	global_load_lds_dwordx4 v[230:231], off
	s_waitcnt vmcnt(8)
	s_waitcnt lgkmcnt(0)
	s_barrier
	s_setprio 1
	s_waitcnt lgkmcnt(0)
	v_mfma_f32_16x16x32_bf16 v[62:65], v[136:139], v[198:201], v[62:65]
	v_mfma_f32_16x16x32_bf16 v[58:61], v[144:147], v[198:201], v[58:61]
	v_mfma_f32_16x16x32_bf16 v[46:49], v[136:139], v[206:209], v[46:49]
	v_mfma_f32_16x16x32_bf16 v[42:45], v[144:147], v[206:209], v[42:45]
	v_mfma_f32_16x16x32_bf16 v[30:33], v[136:139], v[214:217], v[30:33]
	v_mfma_f32_16x16x32_bf16 v[26:29], v[144:147], v[214:217], v[26:29]
	v_mfma_f32_16x16x32_bf16 v[14:17], v[136:139], v[222:225], v[14:17]
	v_mfma_f32_16x16x32_bf16 v[10:13], v[144:147], v[222:225], v[10:13]
	v_mfma_f32_16x16x32_bf16 v[62:65], v[140:143], v[202:205], v[62:65]
	v_mfma_f32_16x16x32_bf16 v[58:61], v[152:155], v[202:205], v[58:61]
	v_mfma_f32_16x16x32_bf16 v[46:49], v[140:143], v[210:213], v[46:49]
	v_mfma_f32_16x16x32_bf16 v[42:45], v[152:155], v[210:213], v[42:45]
	v_mfma_f32_16x16x32_bf16 v[30:33], v[140:143], v[218:221], v[30:33]
	v_mfma_f32_16x16x32_bf16 v[26:29], v[152:155], v[218:221], v[26:29]
	v_mfma_f32_16x16x32_bf16 v[14:17], v[140:143], v[226:229], v[14:17]
	v_mfma_f32_16x16x32_bf16 v[10:13], v[152:155], v[226:229], v[10:13]
	s_setprio 0
	s_setprio 1
	v_mfma_f32_16x16x32_bf16 v[54:57], v[156:159], v[198:201], v[54:57]
	v_mfma_f32_16x16x32_bf16 v[50:53], v[170:173], v[198:201], v[50:53]
	v_mfma_f32_16x16x32_bf16 v[38:41], v[156:159], v[206:209], v[38:41]
	v_mfma_f32_16x16x32_bf16 v[34:37], v[170:173], v[206:209], v[34:37]
	v_mfma_f32_16x16x32_bf16 v[22:25], v[156:159], v[214:217], v[22:25]
	v_mfma_f32_16x16x32_bf16 v[18:21], v[170:173], v[214:217], v[18:21]
	v_mfma_f32_16x16x32_bf16 v[6:9], v[156:159], v[222:225], v[6:9]
	v_mfma_f32_16x16x32_bf16 v[2:5], v[170:173], v[222:225], v[2:5]
	v_mfma_f32_16x16x32_bf16 v[54:57], v[166:169], v[202:205], v[54:57]
	v_mfma_f32_16x16x32_bf16 v[50:53], v[174:177], v[202:205], v[50:53]
	v_mfma_f32_16x16x32_bf16 v[38:41], v[166:169], v[210:213], v[38:41]
	v_mfma_f32_16x16x32_bf16 v[34:37], v[174:177], v[210:213], v[34:37]
	v_mfma_f32_16x16x32_bf16 v[22:25], v[166:169], v[218:221], v[22:25]
	v_mfma_f32_16x16x32_bf16 v[18:21], v[174:177], v[218:221], v[18:21]
	v_mfma_f32_16x16x32_bf16 v[6:9], v[166:169], v[226:229], v[6:9]
	v_mfma_f32_16x16x32_bf16 v[2:5], v[174:177], v[226:229], v[2:5]
	s_setprio 0
	s_barrier
	s_add_i32 s57, 0, 0x18000
	s_add_i32 s58, 0, 0x1c000
	v_add_u32_e32 v152, s57, v149
	v_add_u32_e32 v161, s58, v149
	ds_read_b128 v[136:139], v152
	ds_read_b128 v[140:143], v152 offset:1024
	ds_read_b128 v[144:147], v152 offset:2048
	ds_read_b128 v[152:155], v152 offset:3072
	ds_read_b128 v[156:159], v161
	ds_read_b128 v[166:169], v161 offset:1024
	ds_read_b128 v[170:173], v161 offset:2048
	ds_read_b128 v[174:177], v161 offset:3072
	s_add_u32 s28, s36, 0x40000
	s_addc_u32 s29, s37, 0
	s_mov_b32 m0, s46
	ds_read_b128 v[198:201], v151 offset:32768
	ds_read_b128 v[202:205], v151 offset:33792
	ds_read_b128 v[206:209], v151 offset:34816
	ds_read_b128 v[210:213], v151 offset:35840
	ds_read_b128 v[214:217], v151 offset:36864
	ds_read_b128 v[218:221], v151 offset:37888
	ds_read_b128 v[222:225], v151 offset:38912
	ds_read_b128 v[226:229], v151 offset:39936
	global_load_lds_dwordx4 v0, s[28:29]
	v_lshl_add_u64 v[232:233], s[28:29], 0, v[130:131]
	s_mov_b32 m0, s47
	s_nop 0
	global_load_lds_dwordx4 v[232:233], off
	s_waitcnt vmcnt(8)
	s_waitcnt lgkmcnt(0)
	s_barrier
	s_setprio 1
	s_waitcnt lgkmcnt(0)
	v_mfma_f32_16x16x32_bf16 v[126:129], v[136:139], v[198:201], v[126:129]
	v_mfma_f32_16x16x32_bf16 v[122:125], v[144:147], v[198:201], v[122:125]
	v_mfma_f32_16x16x32_bf16 v[110:113], v[136:139], v[206:209], v[110:113]
	v_mfma_f32_16x16x32_bf16 v[106:109], v[144:147], v[206:209], v[106:109]
	v_mfma_f32_16x16x32_bf16 v[94:97], v[136:139], v[214:217], v[94:97]
	v_mfma_f32_16x16x32_bf16 v[90:93], v[144:147], v[214:217], v[90:93]
	v_mfma_f32_16x16x32_bf16 v[78:81], v[136:139], v[222:225], v[78:81]
	v_mfma_f32_16x16x32_bf16 v[74:77], v[144:147], v[222:225], v[74:77]
	v_mfma_f32_16x16x32_bf16 v[126:129], v[140:143], v[202:205], v[126:129]
	v_mfma_f32_16x16x32_bf16 v[122:125], v[152:155], v[202:205], v[122:125]
	v_mfma_f32_16x16x32_bf16 v[110:113], v[140:143], v[210:213], v[110:113]
	v_mfma_f32_16x16x32_bf16 v[106:109], v[152:155], v[210:213], v[106:109]
	v_mfma_f32_16x16x32_bf16 v[94:97], v[140:143], v[218:221], v[94:97]
	v_mfma_f32_16x16x32_bf16 v[90:93], v[152:155], v[218:221], v[90:93]
	v_mfma_f32_16x16x32_bf16 v[78:81], v[140:143], v[226:229], v[78:81]
	v_mfma_f32_16x16x32_bf16 v[74:77], v[152:155], v[226:229], v[74:77]
	s_setprio 0
	s_setprio 1
	v_mfma_f32_16x16x32_bf16 v[118:121], v[156:159], v[198:201], v[118:121]
	v_mfma_f32_16x16x32_bf16 v[114:117], v[170:173], v[198:201], v[114:117]
	v_mfma_f32_16x16x32_bf16 v[102:105], v[156:159], v[206:209], v[102:105]
	v_mfma_f32_16x16x32_bf16 v[98:101], v[170:173], v[206:209], v[98:101]
	v_mfma_f32_16x16x32_bf16 v[86:89], v[156:159], v[214:217], v[86:89]
	v_mfma_f32_16x16x32_bf16 v[82:85], v[170:173], v[214:217], v[82:85]
	v_mfma_f32_16x16x32_bf16 v[70:73], v[156:159], v[222:225], v[70:73]
	v_mfma_f32_16x16x32_bf16 v[66:69], v[170:173], v[222:225], v[66:69]
	v_mfma_f32_16x16x32_bf16 v[118:121], v[166:169], v[202:205], v[118:121]
	v_mfma_f32_16x16x32_bf16 v[114:117], v[174:177], v[202:205], v[114:117]
	v_mfma_f32_16x16x32_bf16 v[102:105], v[166:169], v[210:213], v[102:105]
	v_mfma_f32_16x16x32_bf16 v[98:101], v[174:177], v[210:213], v[98:101]
	v_mfma_f32_16x16x32_bf16 v[86:89], v[166:169], v[218:221], v[86:89]
	v_mfma_f32_16x16x32_bf16 v[82:85], v[174:177], v[218:221], v[82:85]
	v_mfma_f32_16x16x32_bf16 v[70:73], v[166:169], v[226:229], v[70:73]
	v_mfma_f32_16x16x32_bf16 v[66:69], v[174:177], v[226:229], v[66:69]
	s_setprio 0
	s_barrier
	s_add_i32 s28, s57, s43
	v_lshl_add_u64 v[162:163], v[162:163], 0, s[88:89]
	s_mov_b32 m0, s28
	ds_read_b128 v[198:201], v151 offset:49152
	ds_read_b128 v[202:205], v151 offset:50176
	ds_read_b128 v[206:209], v151 offset:51200
	ds_read_b128 v[210:213], v151 offset:52224
	ds_read_b128 v[214:217], v151 offset:53248
	ds_read_b128 v[218:221], v151 offset:54272
	ds_read_b128 v[222:225], v151 offset:55296
	ds_read_b128 v[226:229], v151 offset:56320
	global_load_lds_dwordx4 v[162:163], off
	s_add_i32 m0, s28, 0x2000
	s_add_u32 s28, s34, 0x40080
	v_lshl_add_u64 v[162:163], v[164:165], 0, s[88:89]
	s_addc_u32 s29, s35, 0
	s_add_i32 s34, s58, s43
	global_load_lds_dwordx4 v[162:163], off
	s_mov_b32 m0, s34
	s_nop 0
	global_load_lds_dwordx4 v0, s[28:29]
	s_add_i32 m0, s34, 0x2000
	s_nop 0
	global_load_lds_dwordx4 v130, s[28:29]
	v_lshl_add_u64 v[162:163], v[178:179], 0, s[88:89]
	s_mov_b32 m0, s49
	s_nop 0
	global_load_lds_dwordx4 v[162:163], off
	v_lshl_add_u64 v[162:163], v[230:231], 0, s[88:89]
	s_mov_b32 m0, s50
	s_nop 0
	global_load_lds_dwordx4 v[162:163], off
	s_waitcnt vmcnt(8)
	s_waitcnt lgkmcnt(0)
	s_barrier
	s_setprio 1
	s_waitcnt lgkmcnt(0)
	v_mfma_f32_16x16x32_bf16 v[62:65], v[136:139], v[198:201], v[62:65]
	v_mfma_f32_16x16x32_bf16 v[58:61], v[144:147], v[198:201], v[58:61]
	v_mfma_f32_16x16x32_bf16 v[46:49], v[136:139], v[206:209], v[46:49]
	v_mfma_f32_16x16x32_bf16 v[42:45], v[144:147], v[206:209], v[42:45]
	v_mfma_f32_16x16x32_bf16 v[30:33], v[136:139], v[214:217], v[30:33]
	v_mfma_f32_16x16x32_bf16 v[26:29], v[144:147], v[214:217], v[26:29]
	v_mfma_f32_16x16x32_bf16 v[14:17], v[136:139], v[222:225], v[14:17]
	v_mfma_f32_16x16x32_bf16 v[10:13], v[144:147], v[222:225], v[10:13]
	v_mfma_f32_16x16x32_bf16 v[62:65], v[140:143], v[202:205], v[62:65]
	v_mfma_f32_16x16x32_bf16 v[58:61], v[152:155], v[202:205], v[58:61]
	v_mfma_f32_16x16x32_bf16 v[46:49], v[140:143], v[210:213], v[46:49]
	v_mfma_f32_16x16x32_bf16 v[42:45], v[152:155], v[210:213], v[42:45]
	v_mfma_f32_16x16x32_bf16 v[30:33], v[140:143], v[218:221], v[30:33]
	v_mfma_f32_16x16x32_bf16 v[26:29], v[152:155], v[218:221], v[26:29]
	v_mfma_f32_16x16x32_bf16 v[14:17], v[140:143], v[226:229], v[14:17]
	v_mfma_f32_16x16x32_bf16 v[10:13], v[152:155], v[226:229], v[10:13]
	s_setprio 0
	s_setprio 1
	v_mfma_f32_16x16x32_bf16 v[54:57], v[156:159], v[198:201], v[54:57]
	v_mfma_f32_16x16x32_bf16 v[50:53], v[170:173], v[198:201], v[50:53]
	v_mfma_f32_16x16x32_bf16 v[38:41], v[156:159], v[206:209], v[38:41]
	v_mfma_f32_16x16x32_bf16 v[34:37], v[170:173], v[206:209], v[34:37]
	v_mfma_f32_16x16x32_bf16 v[22:25], v[156:159], v[214:217], v[22:25]
	v_mfma_f32_16x16x32_bf16 v[18:21], v[170:173], v[214:217], v[18:21]
	v_mfma_f32_16x16x32_bf16 v[6:9], v[156:159], v[222:225], v[6:9]
	v_mfma_f32_16x16x32_bf16 v[2:5], v[170:173], v[222:225], v[2:5]
	v_mfma_f32_16x16x32_bf16 v[54:57], v[166:169], v[202:205], v[54:57]
	v_mfma_f32_16x16x32_bf16 v[50:53], v[174:177], v[202:205], v[50:53]
	v_mfma_f32_16x16x32_bf16 v[38:41], v[166:169], v[210:213], v[38:41]
	v_mfma_f32_16x16x32_bf16 v[34:37], v[174:177], v[210:213], v[34:37]
	v_mfma_f32_16x16x32_bf16 v[22:25], v[166:169], v[218:221], v[22:25]
	v_mfma_f32_16x16x32_bf16 v[18:21], v[174:177], v[218:221], v[18:21]
	v_mfma_f32_16x16x32_bf16 v[6:9], v[166:169], v[226:229], v[6:9]
	v_mfma_f32_16x16x32_bf16 v[2:5], v[174:177], v[226:229], v[2:5]
	s_setprio 0
	s_barrier
	s_add_i32 s56, s56, 2
	s_add_u32 s54, s54, 0x100
	s_addc_u32 s55, s55, 0
	s_cmp_gt_u32 s56, 13
	s_mov_b64 s[28:29], s[30:31]
	s_cbranch_scc0 .LBB0_1154
	s_and_b64 vcc, exec, s[14:15]
	s_cbranch_vccz .LBB0_1157
	s_barrier

.LBB0_1230:
	s_add_u32 s10, s2, 0x2400000
	s_addc_u32 s11, s3, 0
	s_lshl_b32 s9, s12, 5
	s_and_b32 s9, s9, 0x60
	s_add_i32 m0, s36, 0x18000
	v_lshl_add_u64 v[8:9], v[8:9], 0, s[88:89]
	s_lshl_b32 s1, s7, 13
	s_lshl_b32 s14, s9, 7
	s_waitcnt vmcnt(2)
	s_barrier
	global_load_lds_dwordx4 v[8:9], off
	v_lshl_add_u64 v[6:7], v[6:7], 0, s[88:89]
	s_add_i32 m0, s36, 0x1a000
	s_add_i32 s40, s36, 0x8000
	s_add_i32 s41, s36, 0xa000
	global_load_lds_dwordx4 v[6:7], off
	v_lshl_add_u64 v[2:3], v[2:3], 0, s[88:89]
	s_mov_b32 m0, s40
	s_add_u32 s12, s24, 0x40080
	global_load_lds_dwordx4 v[2:3], off
	v_lshl_add_u64 v[2:3], v[4:5], 0, s[88:89]
	s_mov_b32 m0, s41
	s_addc_u32 s13, s25, 0
	global_load_lds_dwordx4 v[2:3], off
	s_add_i32 m0, s36, 0x1c000
	s_nop 0
	global_load_lds_dwordx4 v0, s[12:13]
	v_lshl_add_u64 v[2:3], s[12:13], 0, v[134:135]
	s_add_i32 m0, s36, 0x1e000
	s_cmpk_lt_u32 s6, 0x100
	global_load_lds_dwordx4 v[2:3], off
	v_lshrrev_b32_e32 v3, 1, v10
	v_and_b32_e32 v3, 24, v3
	v_and_b32_e32 v2, 15, v10
	v_lshlrev_b32_e32 v4, 1, v3
	s_waitcnt vmcnt(0)
	v_lshl_or_b32 v146, s7, 6, v2
	v_lshl_or_b32 v2, v2, 6, v4
	v_lshlrev_b32_e32 v4, 2, v10
	v_and_b32_e32 v4, 32, v4
	v_bitop3_b32 v5, v2, s1, v4 bitop3:0xde
	v_bitop3_b32 v147, v2, s14, v4 bitop3:0xde
	v_lshlrev_b32_e32 v2, 14, v11
	v_and_b32_e32 v2, 0xffff8000, v2
	v_or_b32_e32 v148, s9, v3
	v_lshl_add_u32 v2, v12, 11, v2
	v_and_b32_e32 v3, 1, v11
	v_lshl_or_b32 v2, v3, 6, v2
	v_lshl_add_u32 v136, v13, 1, v2
	v_lshlrev_b32_e32 v2, 14, v14
	v_and_b32_e32 v2, 0xffff8000, v2
	s_waitcnt vmcnt(6)
	v_lshl_add_u32 v2, v15, 11, v2
	v_and_b32_e32 v3, 1, v14
	v_lshl_or_b32 v2, v3, 6, v2
	s_cselect_b64 s[12:13], -1, 0
	s_ashr_i32 s42, s28, 31
	s_ashr_i32 s43, s29, 31
	v_mov_b32_e32 v137, v1
	v_lshl_add_u32 v138, v16, 1, v2
	v_mov_b32_e32 v139, v1
	s_mov_b32 s44, 0
	v_add_u32_e32 v149, 0, v5
	s_barrier
	s_branch .LBB0_1233

.LBB0_1240:
	s_add_u32 s24, s22, 0xfffc0080
	s_addc_u32 s25, s23, -1
	s_add_i32 s48, 0, 0x10000
	s_cmp_eq_u32 s47, 12
	s_cselect_b32 s27, s1, s25
	s_cselect_b32 s26, s9, s24
	v_add_u32_e32 v144, s48, v147
	s_cselect_b32 s25, s15, s46
	s_cselect_b32 s24, s17, s45
	s_add_i32 s50, 0, 0x14000
	ds_read_b128 v[140:143], v144
	ds_read_b128 v[150:153], v144 offset:1024
	ds_read_b128 v[154:157], v144 offset:2048
	ds_read_b128 v[166:169], v144 offset:3072
	v_add_u32_e32 v144, s50, v147
	ds_read_b128 v[170:173], v144
	ds_read_b128 v[174:177], v144 offset:1024
	ds_read_b128 v[198:201], v144 offset:2048
	ds_read_b128 v[202:205], v144 offset:3072
	s_add_i32 m0, s36, 0xc000
	ds_read_b128 v[206:209], v149
	ds_read_b128 v[210:213], v149 offset:1024
	ds_read_b128 v[214:217], v149 offset:2048
	ds_read_b128 v[218:221], v149 offset:3072
	ds_read_b128 v[222:225], v149 offset:4096
	ds_read_b128 v[226:229], v149 offset:5120
	ds_read_b128 v[230:233], v149 offset:6144
	ds_read_b128 v[234:237], v149 offset:7168
	global_load_lds_dwordx4 v136, s[22:23]
	s_add_i32 m0, s36, 0xe000
	s_nop 0
	global_load_lds_dwordx4 v138, s[22:23]
	s_waitcnt vmcnt(8)
	s_waitcnt lgkmcnt(0)
	s_barrier
	s_setprio 1
	s_waitcnt lgkmcnt(0)
	v_mfma_f32_16x16x32_bf16 v[126:129], v[140:143], v[206:209], v[126:129]
	v_mfma_f32_16x16x32_bf16 v[122:125], v[154:157], v[206:209], v[122:125]
	v_mfma_f32_16x16x32_bf16 v[110:113], v[140:143], v[214:217], v[110:113]
	v_mfma_f32_16x16x32_bf16 v[106:109], v[154:157], v[214:217], v[106:109]
	v_mfma_f32_16x16x32_bf16 v[94:97], v[140:143], v[222:225], v[94:97]
	v_mfma_f32_16x16x32_bf16 v[90:93], v[154:157], v[222:225], v[90:93]
	v_mfma_f32_16x16x32_bf16 v[78:81], v[140:143], v[230:233], v[78:81]
	v_mfma_f32_16x16x32_bf16 v[74:77], v[154:157], v[230:233], v[74:77]
	v_mfma_f32_16x16x32_bf16 v[126:129], v[150:153], v[210:213], v[126:129]
	v_mfma_f32_16x16x32_bf16 v[122:125], v[166:169], v[210:213], v[122:125]
	v_mfma_f32_16x16x32_bf16 v[110:113], v[150:153], v[218:221], v[110:113]
	v_mfma_f32_16x16x32_bf16 v[106:109], v[166:169], v[218:221], v[106:109]
	v_mfma_f32_16x16x32_bf16 v[94:97], v[150:153], v[226:229], v[94:97]
	v_mfma_f32_16x16x32_bf16 v[90:93], v[166:169], v[226:229], v[90:93]
	v_mfma_f32_16x16x32_bf16 v[78:81], v[150:153], v[234:237], v[78:81]
	v_mfma_f32_16x16x32_bf16 v[74:77], v[166:169], v[234:237], v[74:77]
	s_setprio 0
	s_setprio 1
	v_mfma_f32_16x16x32_bf16 v[118:121], v[170:173], v[206:209], v[118:121]
	v_mfma_f32_16x16x32_bf16 v[114:117], v[198:201], v[206:209], v[114:117]
	v_mfma_f32_16x16x32_bf16 v[102:105], v[170:173], v[214:217], v[102:105]
	v_mfma_f32_16x16x32_bf16 v[98:101], v[198:201], v[214:217], v[98:101]
	v_mfma_f32_16x16x32_bf16 v[86:89], v[170:173], v[222:225], v[86:89]
	v_mfma_f32_16x16x32_bf16 v[82:85], v[198:201], v[222:225], v[82:85]
	v_mfma_f32_16x16x32_bf16 v[70:73], v[170:173], v[230:233], v[70:73]
	v_mfma_f32_16x16x32_bf16 v[66:69], v[198:201], v[230:233], v[66:69]
	v_mfma_f32_16x16x32_bf16 v[118:121], v[174:177], v[210:213], v[118:121]
	v_mfma_f32_16x16x32_bf16 v[114:117], v[202:205], v[210:213], v[114:117]
	v_mfma_f32_16x16x32_bf16 v[102:105], v[174:177], v[218:221], v[102:105]
	v_mfma_f32_16x16x32_bf16 v[98:101], v[202:205], v[218:221], v[98:101]
	v_mfma_f32_16x16x32_bf16 v[86:89], v[174:177], v[226:229], v[86:89]
	v_mfma_f32_16x16x32_bf16 v[82:85], v[202:205], v[226:229], v[82:85]
	v_mfma_f32_16x16x32_bf16 v[70:73], v[174:177], v[234:237], v[70:73]
	v_mfma_f32_16x16x32_bf16 v[66:69], v[202:205], v[234:237], v[66:69]
	s_setprio 0
	s_barrier
	s_add_i32 s48, s48, s35
	v_lshl_add_u64 v[144:145], s[24:25], 0, v[0:1]
	s_mov_b32 m0, s48
	ds_read_b128 v[206:209], v149 offset:16384
	ds_read_b128 v[210:213], v149 offset:17408
	ds_read_b128 v[214:217], v149 offset:18432
	ds_read_b128 v[218:221], v149 offset:19456
	ds_read_b128 v[222:225], v149 offset:20480
	ds_read_b128 v[226:229], v149 offset:21504
	ds_read_b128 v[230:233], v149 offset:22528
	ds_read_b128 v[234:237], v149 offset:23552
	global_load_lds_dwordx4 v[144:145], off
	s_add_i32 m0, s48, 0x2000
	s_add_u32 s48, s24, 0x40000
	v_lshl_add_u64 v[158:159], s[24:25], 0, v[134:135]
	s_addc_u32 s49, s25, 0
	s_add_i32 s50, s50, s35
	global_load_lds_dwordx4 v[158:159], off
	s_mov_b32 m0, s50
	v_lshl_add_u64 v[164:165], s[26:27], 0, v[132:133]
	global_load_lds_dwordx4 v0, s[48:49]
	s_add_i32 m0, s50, 0x2000
	s_nop 0
	global_load_lds_dwordx4 v134, s[48:49]
	v_lshl_add_u64 v[162:163], s[26:27], 0, v[130:131]
	s_mov_b32 m0, s36
	s_nop 0
	global_load_lds_dwordx4 v[162:163], off
	s_mov_b32 m0, s37
	s_nop 0
	global_load_lds_dwordx4 v[164:165], off
	s_waitcnt vmcnt(8)
	s_waitcnt lgkmcnt(0)
	s_barrier
	s_setprio 1
	s_waitcnt lgkmcnt(0)
	v_mfma_f32_16x16x32_bf16 v[62:65], v[140:143], v[206:209], v[62:65]
	v_mfma_f32_16x16x32_bf16 v[58:61], v[154:157], v[206:209], v[58:61]
	v_mfma_f32_16x16x32_bf16 v[46:49], v[140:143], v[214:217], v[46:49]
	v_mfma_f32_16x16x32_bf16 v[42:45], v[154:157], v[214:217], v[42:45]
	v_mfma_f32_16x16x32_bf16 v[30:33], v[140:143], v[222:225], v[30:33]
	v_mfma_f32_16x16x32_bf16 v[26:29], v[154:157], v[222:225], v[26:29]
	v_mfma_f32_16x16x32_bf16 v[14:17], v[140:143], v[230:233], v[14:17]
	v_mfma_f32_16x16x32_bf16 v[10:13], v[154:157], v[230:233], v[10:13]
	v_mfma_f32_16x16x32_bf16 v[62:65], v[150:153], v[210:213], v[62:65]
	v_mfma_f32_16x16x32_bf16 v[58:61], v[166:169], v[210:213], v[58:61]
	v_mfma_f32_16x16x32_bf16 v[46:49], v[150:153], v[218:221], v[46:49]
	v_mfma_f32_16x16x32_bf16 v[42:45], v[166:169], v[218:221], v[42:45]
	v_mfma_f32_16x16x32_bf16 v[30:33], v[150:153], v[226:229], v[30:33]
	v_mfma_f32_16x16x32_bf16 v[26:29], v[166:169], v[226:229], v[26:29]
	v_mfma_f32_16x16x32_bf16 v[14:17], v[150:153], v[234:237], v[14:17]
	v_mfma_f32_16x16x32_bf16 v[10:13], v[166:169], v[234:237], v[10:13]
	s_setprio 0
	s_setprio 1
	v_mfma_f32_16x16x32_bf16 v[54:57], v[170:173], v[206:209], v[54:57]
	v_mfma_f32_16x16x32_bf16 v[50:53], v[198:201], v[206:209], v[50:53]
	v_mfma_f32_16x16x32_bf16 v[38:41], v[170:173], v[214:217], v[38:41]
	v_mfma_f32_16x16x32_bf16 v[34:37], v[198:201], v[214:217], v[34:37]
	v_mfma_f32_16x16x32_bf16 v[22:25], v[170:173], v[222:225], v[22:25]
	v_mfma_f32_16x16x32_bf16 v[18:21], v[198:201], v[222:225], v[18:21]
	v_mfma_f32_16x16x32_bf16 v[6:9], v[170:173], v[230:233], v[6:9]
	v_mfma_f32_16x16x32_bf16 v[2:5], v[198:201], v[230:233], v[2:5]
	v_mfma_f32_16x16x32_bf16 v[54:57], v[174:177], v[210:213], v[54:57]
	v_mfma_f32_16x16x32_bf16 v[50:53], v[202:205], v[210:213], v[50:53]
	v_mfma_f32_16x16x32_bf16 v[38:41], v[174:177], v[218:221], v[38:41]
	v_mfma_f32_16x16x32_bf16 v[34:37], v[202:205], v[218:221], v[34:37]
	v_mfma_f32_16x16x32_bf16 v[22:25], v[174:177], v[226:229], v[22:25]
	v_mfma_f32_16x16x32_bf16 v[18:21], v[202:205], v[226:229], v[18:21]
	v_mfma_f32_16x16x32_bf16 v[6:9], v[174:177], v[234:237], v[6:9]
	v_mfma_f32_16x16x32_bf16 v[2:5], v[202:205], v[234:237], v[2:5]
	s_setprio 0
	s_barrier
	s_add_i32 s48, 0, 0x18000
	v_add_u32_e32 v161, s48, v147
	s_add_i32 s49, 0, 0x1c000
	ds_read_b128 v[140:143], v161
	ds_read_b128 v[150:153], v161 offset:1024
	ds_read_b128 v[154:157], v161 offset:2048
	ds_read_b128 v[166:169], v161 offset:3072
	v_add_u32_e32 v161, s49, v147
	ds_read_b128 v[170:173], v161
	ds_read_b128 v[174:177], v161 offset:1024
	ds_read_b128 v[198:201], v161 offset:2048
	ds_read_b128 v[202:205], v161 offset:3072
	s_add_u32 s26, s26, 0x40000
	s_addc_u32 s27, s27, 0
	s_mov_b32 m0, s38
	ds_read_b128 v[206:209], v149 offset:32768
	ds_read_b128 v[210:213], v149 offset:33792
	ds_read_b128 v[214:217], v149 offset:34816
	ds_read_b128 v[218:221], v149 offset:35840
	ds_read_b128 v[222:225], v149 offset:36864
	ds_read_b128 v[226:229], v149 offset:37888
	ds_read_b128 v[230:233], v149 offset:38912
	ds_read_b128 v[234:237], v149 offset:39936
	global_load_lds_dwordx4 v130, s[26:27]
	v_lshl_add_u64 v[178:179], s[26:27], 0, v[132:133]
	s_mov_b32 m0, s39
	s_nop 0
	global_load_lds_dwordx4 v[178:179], off
	s_waitcnt vmcnt(8)
	s_waitcnt lgkmcnt(0)
	s_barrier
	s_setprio 1
	s_waitcnt lgkmcnt(0)
	v_mfma_f32_16x16x32_bf16 v[126:129], v[140:143], v[206:209], v[126:129]
	v_mfma_f32_16x16x32_bf16 v[122:125], v[154:157], v[206:209], v[122:125]
	v_mfma_f32_16x16x32_bf16 v[110:113], v[140:143], v[214:217], v[110:113]
	v_mfma_f32_16x16x32_bf16 v[106:109], v[154:157], v[214:217], v[106:109]
	v_mfma_f32_16x16x32_bf16 v[94:97], v[140:143], v[222:225], v[94:97]
	v_mfma_f32_16x16x32_bf16 v[90:93], v[154:157], v[222:225], v[90:93]
	v_mfma_f32_16x16x32_bf16 v[78:81], v[140:143], v[230:233], v[78:81]
	v_mfma_f32_16x16x32_bf16 v[74:77], v[154:157], v[230:233], v[74:77]
	v_mfma_f32_16x16x32_bf16 v[126:129], v[150:153], v[210:213], v[126:129]
	v_mfma_f32_16x16x32_bf16 v[122:125], v[166:169], v[210:213], v[122:125]
	v_mfma_f32_16x16x32_bf16 v[110:113], v[150:153], v[218:221], v[110:113]
	v_mfma_f32_16x16x32_bf16 v[106:109], v[166:169], v[218:221], v[106:109]
	v_mfma_f32_16x16x32_bf16 v[94:97], v[150:153], v[226:229], v[94:97]
	v_mfma_f32_16x16x32_bf16 v[90:93], v[166:169], v[226:229], v[90:93]
	v_mfma_f32_16x16x32_bf16 v[78:81], v[150:153], v[234:237], v[78:81]
	v_mfma_f32_16x16x32_bf16 v[74:77], v[166:169], v[234:237], v[74:77]
	s_setprio 0
	s_setprio 1
	v_mfma_f32_16x16x32_bf16 v[118:121], v[170:173], v[206:209], v[118:121]
	v_mfma_f32_16x16x32_bf16 v[114:117], v[198:201], v[206:209], v[114:117]
	v_mfma_f32_16x16x32_bf16 v[102:105], v[170:173], v[214:217], v[102:105]
	v_mfma_f32_16x16x32_bf16 v[98:101], v[198:201], v[214:217], v[98:101]
	v_mfma_f32_16x16x32_bf16 v[86:89], v[170:173], v[222:225], v[86:89]
	v_mfma_f32_16x16x32_bf16 v[82:85], v[198:201], v[222:225], v[82:85]
	v_mfma_f32_16x16x32_bf16 v[70:73], v[170:173], v[230:233], v[70:73]
	v_mfma_f32_16x16x32_bf16 v[66:69], v[198:201], v[230:233], v[66:69]
	v_mfma_f32_16x16x32_bf16 v[118:121], v[174:177], v[210:213], v[118:121]
	v_mfma_f32_16x16x32_bf16 v[114:117], v[202:205], v[210:213], v[114:117]
	v_mfma_f32_16x16x32_bf16 v[102:105], v[174:177], v[218:221], v[102:105]
	v_mfma_f32_16x16x32_bf16 v[98:101], v[202:205], v[218:221], v[98:101]
	v_mfma_f32_16x16x32_bf16 v[86:89], v[174:177], v[226:229], v[86:89]
	v_mfma_f32_16x16x32_bf16 v[82:85], v[202:205], v[226:229], v[82:85]
	v_mfma_f32_16x16x32_bf16 v[70:73], v[174:177], v[234:237], v[70:73]
	v_mfma_f32_16x16x32_bf16 v[66:69], v[202:205], v[234:237], v[66:69]
	s_setprio 0
	s_barrier
	s_add_i32 s26, s48, s35
	v_lshl_add_u64 v[144:145], v[144:145], 0, s[88:89]
	s_mov_b32 m0, s26
	ds_read_b128 v[206:209], v149 offset:49152
	ds_read_b128 v[210:213], v149 offset:50176
	ds_read_b128 v[214:217], v149 offset:51200
	ds_read_b128 v[218:221], v149 offset:52224
	ds_read_b128 v[222:225], v149 offset:53248
	ds_read_b128 v[226:229], v149 offset:54272
	ds_read_b128 v[230:233], v149 offset:55296
	ds_read_b128 v[234:237], v149 offset:56320
	global_load_lds_dwordx4 v[144:145], off
	s_add_i32 m0, s26, 0x2000
	s_add_u32 s24, s24, 0x40080
	v_lshl_add_u64 v[144:145], v[158:159], 0, s[88:89]
	s_addc_u32 s25, s25, 0
	s_add_i32 s26, s49, s35
	global_load_lds_dwordx4 v[144:145], off
	s_mov_b32 m0, s26
	s_nop 0
	global_load_lds_dwordx4 v0, s[24:25]
	s_add_i32 m0, s26, 0x2000
	s_nop 0
	global_load_lds_dwordx4 v134, s[24:25]
	v_lshl_add_u64 v[144:145], v[162:163], 0, s[88:89]
	s_mov_b32 m0, s40
	s_nop 0
	global_load_lds_dwordx4 v[144:145], off
	v_lshl_add_u64 v[144:145], v[164:165], 0, s[88:89]
	s_mov_b32 m0, s41
	s_nop 0
	global_load_lds_dwordx4 v[144:145], off
	s_waitcnt vmcnt(8)
	s_waitcnt lgkmcnt(0)
	s_barrier
	s_setprio 1
	s_waitcnt lgkmcnt(0)
	v_mfma_f32_16x16x32_bf16 v[62:65], v[140:143], v[206:209], v[62:65]
	v_mfma_f32_16x16x32_bf16 v[58:61], v[154:157], v[206:209], v[58:61]
	v_mfma_f32_16x16x32_bf16 v[46:49], v[140:143], v[214:217], v[46:49]
	v_mfma_f32_16x16x32_bf16 v[42:45], v[154:157], v[214:217], v[42:45]
	v_mfma_f32_16x16x32_bf16 v[30:33], v[140:143], v[222:225], v[30:33]
	v_mfma_f32_16x16x32_bf16 v[26:29], v[154:157], v[222:225], v[26:29]
	v_mfma_f32_16x16x32_bf16 v[14:17], v[140:143], v[230:233], v[14:17]
	v_mfma_f32_16x16x32_bf16 v[10:13], v[154:157], v[230:233], v[10:13]
	v_mfma_f32_16x16x32_bf16 v[62:65], v[150:153], v[210:213], v[62:65]
	v_mfma_f32_16x16x32_bf16 v[58:61], v[166:169], v[210:213], v[58:61]
	v_mfma_f32_16x16x32_bf16 v[46:49], v[150:153], v[218:221], v[46:49]
	v_mfma_f32_16x16x32_bf16 v[42:45], v[166:169], v[218:221], v[42:45]
	v_mfma_f32_16x16x32_bf16 v[30:33], v[150:153], v[226:229], v[30:33]
	v_mfma_f32_16x16x32_bf16 v[26:29], v[166:169], v[226:229], v[26:29]
	v_mfma_f32_16x16x32_bf16 v[14:17], v[150:153], v[234:237], v[14:17]
	v_mfma_f32_16x16x32_bf16 v[10:13], v[166:169], v[234:237], v[10:13]
	s_setprio 0
	s_setprio 1
	v_mfma_f32_16x16x32_bf16 v[54:57], v[170:173], v[206:209], v[54:57]
	v_mfma_f32_16x16x32_bf16 v[50:53], v[198:201], v[206:209], v[50:53]
	v_mfma_f32_16x16x32_bf16 v[38:41], v[170:173], v[214:217], v[38:41]
	v_mfma_f32_16x16x32_bf16 v[34:37], v[198:201], v[214:217], v[34:37]
	v_mfma_f32_16x16x32_bf16 v[22:25], v[170:173], v[222:225], v[22:25]
	v_mfma_f32_16x16x32_bf16 v[18:21], v[198:201], v[222:225], v[18:21]
	v_mfma_f32_16x16x32_bf16 v[6:9], v[170:173], v[230:233], v[6:9]
	v_mfma_f32_16x16x32_bf16 v[2:5], v[198:201], v[230:233], v[2:5]
	v_mfma_f32_16x16x32_bf16 v[54:57], v[174:177], v[210:213], v[54:57]
	v_mfma_f32_16x16x32_bf16 v[50:53], v[202:205], v[210:213], v[50:53]
	v_mfma_f32_16x16x32_bf16 v[38:41], v[174:177], v[218:221], v[38:41]
	v_mfma_f32_16x16x32_bf16 v[34:37], v[202:205], v[218:221], v[34:37]
	v_mfma_f32_16x16x32_bf16 v[22:25], v[174:177], v[226:229], v[22:25]
	v_mfma_f32_16x16x32_bf16 v[18:21], v[202:205], v[226:229], v[18:21]
	v_mfma_f32_16x16x32_bf16 v[6:9], v[174:177], v[234:237], v[6:9]
	v_mfma_f32_16x16x32_bf16 v[2:5], v[202:205], v[234:237], v[2:5]
	s_setprio 0
	s_barrier
	s_add_i32 s47, s47, 2
	s_add_u32 s22, s22, 0x100
	s_addc_u32 s23, s23, 0
	s_add_u32 s45, s45, 0x100
	s_addc_u32 s46, s46, 0
	s_cmp_gt_u32 s47, 13
	s_cbranch_scc0 .LBB0_1240
	s_and_b64 vcc, exec, s[12:13]
	s_cbranch_vccz .LBB0_1243
	s_barrier

.LBB0_1332:
	s_add_u32 s12, s2, 0xbe00000
	s_addc_u32 s13, s3, 0
	v_readlane_b32 s14, v254, 17
	v_readlane_b32 s15, v254, 18
	s_bitcmp1_b32 s14, 0
	s_cselect_b64 s[14:15], -1, 0
	s_and_b32 s48, s6, 3
	s_add_i32 m0, s44, 0x18000
	v_lshl_add_u64 v[8:9], v[8:9], 0, s[88:89]
	s_xor_b64 s[14:15], s[14:15], -1
	s_lshl_b32 s6, s7, 13
	s_lshl_b32 s9, s48, 12
	s_waitcnt vmcnt(2)
	s_barrier
	global_load_lds_dwordx4 v[8:9], off
	v_lshl_add_u64 v[6:7], v[6:7], 0, s[88:89]
	s_add_i32 m0, s44, 0x1a000
	s_add_i32 s49, s44, 0x8000
	s_add_i32 s50, s44, 0xa000
	global_load_lds_dwordx4 v[6:7], off
	v_lshl_add_u64 v[2:3], v[2:3], 0, s[88:89]
	s_mov_b32 m0, s49
	s_add_u32 s16, s30, 0x100080
	global_load_lds_dwordx4 v[2:3], off
	v_lshl_add_u64 v[2:3], v[4:5], 0, s[88:89]
	s_mov_b32 m0, s50
	s_addc_u32 s17, s31, 0
	global_load_lds_dwordx4 v[2:3], off
	s_add_i32 m0, s44, 0x1c000
	s_nop 0
	global_load_lds_dwordx4 v0, s[16:17]
	v_lshl_add_u64 v[2:3], s[16:17], 0, v[130:131]
	s_add_i32 m0, s44, 0x1e000
	s_cmpk_lt_u32 s8, 0x100
	global_load_lds_dwordx4 v[2:3], off
	v_bfe_u32 v2, v10, 4, 2
	v_and_b32_e32 v3, 15, v10
	v_lshlrev_b32_e32 v4, 4, v2
	s_waitcnt vmcnt(0)
	v_lshl_or_b32 v150, s7, 6, v3
	v_lshl_or_b32 v3, v3, 6, v4
	v_lshlrev_b32_e32 v4, 2, v10
	v_and_b32_e32 v4, 32, v4
	v_bitop3_b32 v5, v3, s6, v4 bitop3:0xde
	v_bitop3_b32 v151, v3, s9, v4 bitop3:0xde
	v_lshlrev_b32_e32 v3, 2, v2
	v_cmp_eq_u32_e64 s[6:7], 0, v2
	v_lshlrev_b32_e32 v2, 15, v11
	v_and_b32_e32 v2, 0x7fff0000, v2
	v_lshl_add_u32 v2, v12, 12, v2
	v_or_b32_e32 v2, v2, v13
	v_lshl_or_b32 v152, s48, 5, v3
	v_add_lshl_u32 v2, v2, v14, 1
	v_mov_b32_e32 v3, v1
	s_mov_b64 s[8:9], 0x100080
	v_lshl_add_u64 v[132:133], v[2:3], 0, s[8:9]
	v_lshlrev_b32_e32 v2, 15, v15
	v_and_b32_e32 v2, 0x7fff0000, v2
	v_lshl_add_u32 v2, v16, 12, v2
	s_waitcnt vmcnt(6)
	v_or_b32_e32 v2, v2, v17
	v_add_lshl_u32 v2, v2, v18, 1
	s_cselect_b64 s[16:17], -1, 0
	s_mov_b32 s51, 0
	s_ashr_i32 s52, s33, 31
	s_ashr_i32 s53, s38, 31
	v_lshl_add_u64 v[134:135], v[2:3], 0, s[8:9]
	v_add_u32_e32 v153, 0, v5
	s_barrier
	s_branch .LBB0_1335

.LBB0_1342:
	s_add_u32 s30, s28, 0x100
	s_addc_u32 s31, s29, 0
	s_add_i32 s57, 0, 0x10000
	s_cmp_eq_u32 s56, 60
	s_cselect_b32 s37, s11, s31
	s_cselect_b32 s36, s21, s30
	v_add_u32_e32 v148, s57, v151
	s_cselect_b32 s35, s19, s55
	s_cselect_b32 s34, s27, s54
	s_add_i32 s58, 0, 0x14000
	ds_read_b128 v[136:139], v148
	ds_read_b128 v[140:143], v148 offset:1024
	ds_read_b128 v[144:147], v148 offset:2048
	ds_read_b128 v[154:157], v148 offset:3072
	v_add_u32_e32 v148, s58, v151
	ds_read_b128 v[166:169], v148
	ds_read_b128 v[170:173], v148 offset:1024
	ds_read_b128 v[174:177], v148 offset:2048
	ds_read_b128 v[198:201], v148 offset:3072
	s_add_i32 m0, s44, 0xc000
	ds_read_b128 v[202:205], v153
	ds_read_b128 v[206:209], v153 offset:1024
	ds_read_b128 v[210:213], v153 offset:2048
	ds_read_b128 v[214:217], v153 offset:3072
	ds_read_b128 v[218:221], v153 offset:4096
	ds_read_b128 v[222:225], v153 offset:5120
	ds_read_b128 v[226:229], v153 offset:6144
	ds_read_b128 v[230:233], v153 offset:7168
	global_load_lds_dwordx4 v132, s[28:29]
	s_add_i32 m0, s44, 0xe000
	s_nop 0
	global_load_lds_dwordx4 v134, s[28:29]
	s_waitcnt vmcnt(8)
	s_waitcnt lgkmcnt(0)
	s_barrier
	s_setprio 1
	s_waitcnt lgkmcnt(0)
	v_mfma_f32_16x16x32_bf16 v[126:129], v[136:139], v[202:205], v[126:129]
	v_mfma_f32_16x16x32_bf16 v[122:125], v[144:147], v[202:205], v[122:125]
	v_mfma_f32_16x16x32_bf16 v[110:113], v[136:139], v[210:213], v[110:113]
	v_mfma_f32_16x16x32_bf16 v[106:109], v[144:147], v[210:213], v[106:109]
	v_mfma_f32_16x16x32_bf16 v[94:97], v[136:139], v[218:221], v[94:97]
	v_mfma_f32_16x16x32_bf16 v[90:93], v[144:147], v[218:221], v[90:93]
	v_mfma_f32_16x16x32_bf16 v[78:81], v[136:139], v[226:229], v[78:81]
	v_mfma_f32_16x16x32_bf16 v[74:77], v[144:147], v[226:229], v[74:77]
	v_mfma_f32_16x16x32_bf16 v[126:129], v[140:143], v[206:209], v[126:129]
	v_mfma_f32_16x16x32_bf16 v[122:125], v[154:157], v[206:209], v[122:125]
	v_mfma_f32_16x16x32_bf16 v[110:113], v[140:143], v[214:217], v[110:113]
	v_mfma_f32_16x16x32_bf16 v[106:109], v[154:157], v[214:217], v[106:109]
	v_mfma_f32_16x16x32_bf16 v[94:97], v[140:143], v[222:225], v[94:97]
	v_mfma_f32_16x16x32_bf16 v[90:93], v[154:157], v[222:225], v[90:93]
	v_mfma_f32_16x16x32_bf16 v[78:81], v[140:143], v[230:233], v[78:81]
	v_mfma_f32_16x16x32_bf16 v[74:77], v[154:157], v[230:233], v[74:77]
	s_setprio 0
	s_setprio 1
	v_mfma_f32_16x16x32_bf16 v[118:121], v[166:169], v[202:205], v[118:121]
	v_mfma_f32_16x16x32_bf16 v[114:117], v[174:177], v[202:205], v[114:117]
	v_mfma_f32_16x16x32_bf16 v[102:105], v[166:169], v[210:213], v[102:105]
	v_mfma_f32_16x16x32_bf16 v[98:101], v[174:177], v[210:213], v[98:101]
	v_mfma_f32_16x16x32_bf16 v[86:89], v[166:169], v[218:221], v[86:89]
	v_mfma_f32_16x16x32_bf16 v[82:85], v[174:177], v[218:221], v[82:85]
	v_mfma_f32_16x16x32_bf16 v[70:73], v[166:169], v[226:229], v[70:73]
	v_mfma_f32_16x16x32_bf16 v[66:69], v[174:177], v[226:229], v[66:69]
	v_mfma_f32_16x16x32_bf16 v[118:121], v[170:173], v[206:209], v[118:121]
	v_mfma_f32_16x16x32_bf16 v[114:117], v[198:201], v[206:209], v[114:117]
	v_mfma_f32_16x16x32_bf16 v[102:105], v[170:173], v[214:217], v[102:105]
	v_mfma_f32_16x16x32_bf16 v[98:101], v[198:201], v[214:217], v[98:101]
	v_mfma_f32_16x16x32_bf16 v[86:89], v[170:173], v[222:225], v[86:89]
	v_mfma_f32_16x16x32_bf16 v[82:85], v[198:201], v[222:225], v[82:85]
	v_mfma_f32_16x16x32_bf16 v[70:73], v[170:173], v[230:233], v[70:73]
	v_mfma_f32_16x16x32_bf16 v[66:69], v[198:201], v[230:233], v[66:69]
	s_setprio 0
	s_barrier
	s_add_i32 s28, s57, s43
	v_lshl_add_u64 v[148:149], s[34:35], 0, v[0:1]
	s_mov_b32 m0, s28
	ds_read_b128 v[202:205], v153 offset:16384
	ds_read_b128 v[206:209], v153 offset:17408
	ds_read_b128 v[210:213], v153 offset:18432
	ds_read_b128 v[214:217], v153 offset:19456
	ds_read_b128 v[218:221], v153 offset:20480
	ds_read_b128 v[222:225], v153 offset:21504
	ds_read_b128 v[226:229], v153 offset:22528
	ds_read_b128 v[230:233], v153 offset:23552
	global_load_lds_dwordx4 v[148:149], off
	s_add_i32 m0, s28, 0x2000
	s_add_u32 s28, s34, 0x100000
	v_lshl_add_u64 v[158:159], s[34:35], 0, v[130:131]
	s_addc_u32 s29, s35, 0
	s_add_i32 s57, s58, s43
	global_load_lds_dwordx4 v[158:159], off
	s_mov_b32 m0, s57
	v_lshl_add_u64 v[164:165], s[36:37], 0, v[130:131]
	global_load_lds_dwordx4 v0, s[28:29]
	s_add_i32 m0, s57, 0x2000
	s_nop 0
	global_load_lds_dwordx4 v130, s[28:29]
	v_lshl_add_u64 v[162:163], s[36:37], 0, v[0:1]
	s_mov_b32 m0, s44
	s_nop 0
	global_load_lds_dwordx4 v[162:163], off
	s_mov_b32 m0, s45
	s_nop 0
	global_load_lds_dwordx4 v[164:165], off
	s_waitcnt vmcnt(8)
	s_waitcnt lgkmcnt(0)
	s_barrier
	s_setprio 1
	s_waitcnt lgkmcnt(0)
	v_mfma_f32_16x16x32_bf16 v[62:65], v[136:139], v[202:205], v[62:65]
	v_mfma_f32_16x16x32_bf16 v[58:61], v[144:147], v[202:205], v[58:61]
	v_mfma_f32_16x16x32_bf16 v[46:49], v[136:139], v[210:213], v[46:49]
	v_mfma_f32_16x16x32_bf16 v[42:45], v[144:147], v[210:213], v[42:45]
	v_mfma_f32_16x16x32_bf16 v[30:33], v[136:139], v[218:221], v[30:33]
	v_mfma_f32_16x16x32_bf16 v[26:29], v[144:147], v[218:221], v[26:29]
	v_mfma_f32_16x16x32_bf16 v[14:17], v[136:139], v[226:229], v[14:17]
	v_mfma_f32_16x16x32_bf16 v[10:13], v[144:147], v[226:229], v[10:13]
	v_mfma_f32_16x16x32_bf16 v[62:65], v[140:143], v[206:209], v[62:65]
	v_mfma_f32_16x16x32_bf16 v[58:61], v[154:157], v[206:209], v[58:61]
	v_mfma_f32_16x16x32_bf16 v[46:49], v[140:143], v[214:217], v[46:49]
	v_mfma_f32_16x16x32_bf16 v[42:45], v[154:157], v[214:217], v[42:45]
	v_mfma_f32_16x16x32_bf16 v[30:33], v[140:143], v[222:225], v[30:33]
	v_mfma_f32_16x16x32_bf16 v[26:29], v[154:157], v[222:225], v[26:29]
	v_mfma_f32_16x16x32_bf16 v[14:17], v[140:143], v[230:233], v[14:17]
	v_mfma_f32_16x16x32_bf16 v[10:13], v[154:157], v[230:233], v[10:13]
	s_setprio 0
	s_setprio 1
	v_mfma_f32_16x16x32_bf16 v[54:57], v[166:169], v[202:205], v[54:57]
	v_mfma_f32_16x16x32_bf16 v[50:53], v[174:177], v[202:205], v[50:53]
	v_mfma_f32_16x16x32_bf16 v[38:41], v[166:169], v[210:213], v[38:41]
	v_mfma_f32_16x16x32_bf16 v[34:37], v[174:177], v[210:213], v[34:37]
	v_mfma_f32_16x16x32_bf16 v[22:25], v[166:169], v[218:221], v[22:25]
	v_mfma_f32_16x16x32_bf16 v[18:21], v[174:177], v[218:221], v[18:21]
	v_mfma_f32_16x16x32_bf16 v[6:9], v[166:169], v[226:229], v[6:9]
	v_mfma_f32_16x16x32_bf16 v[2:5], v[174:177], v[226:229], v[2:5]
	v_mfma_f32_16x16x32_bf16 v[54:57], v[170:173], v[206:209], v[54:57]
	v_mfma_f32_16x16x32_bf16 v[50:53], v[198:201], v[206:209], v[50:53]
	v_mfma_f32_16x16x32_bf16 v[38:41], v[170:173], v[214:217], v[38:41]
	v_mfma_f32_16x16x32_bf16 v[34:37], v[198:201], v[214:217], v[34:37]
	v_mfma_f32_16x16x32_bf16 v[22:25], v[170:173], v[222:225], v[22:25]
	v_mfma_f32_16x16x32_bf16 v[18:21], v[198:201], v[222:225], v[18:21]
	v_mfma_f32_16x16x32_bf16 v[6:9], v[170:173], v[230:233], v[6:9]
	v_mfma_f32_16x16x32_bf16 v[2:5], v[198:201], v[230:233], v[2:5]
	s_setprio 0
	s_barrier
	s_add_i32 s57, 0, 0x18000
	s_add_i32 s58, 0, 0x1c000
	v_add_u32_e32 v154, s57, v151
	v_add_u32_e32 v161, s58, v151
	ds_read_b128 v[136:139], v154
	ds_read_b128 v[140:143], v154 offset:1024
	ds_read_b128 v[144:147], v154 offset:2048
	ds_read_b128 v[154:157], v154 offset:3072
	ds_read_b128 v[166:169], v161
	ds_read_b128 v[170:173], v161 offset:1024
	ds_read_b128 v[174:177], v161 offset:2048
	ds_read_b128 v[198:201], v161 offset:3072
	s_add_u32 s28, s36, 0x100000
	s_addc_u32 s29, s37, 0
	s_mov_b32 m0, s46
	ds_read_b128 v[202:205], v153 offset:32768
	ds_read_b128 v[206:209], v153 offset:33792
	ds_read_b128 v[210:213], v153 offset:34816
	ds_read_b128 v[214:217], v153 offset:35840
	ds_read_b128 v[218:221], v153 offset:36864
	ds_read_b128 v[222:225], v153 offset:37888
	ds_read_b128 v[226:229], v153 offset:38912
	ds_read_b128 v[230:233], v153 offset:39936
	global_load_lds_dwordx4 v0, s[28:29]
	v_lshl_add_u64 v[178:179], s[28:29], 0, v[130:131]
	s_mov_b32 m0, s47
	s_nop 0
	global_load_lds_dwordx4 v[178:179], off
	s_waitcnt vmcnt(8)
	s_waitcnt lgkmcnt(0)
	s_barrier
	s_setprio 1
	s_waitcnt lgkmcnt(0)
	v_mfma_f32_16x16x32_bf16 v[126:129], v[136:139], v[202:205], v[126:129]
	v_mfma_f32_16x16x32_bf16 v[122:125], v[144:147], v[202:205], v[122:125]
	v_mfma_f32_16x16x32_bf16 v[110:113], v[136:139], v[210:213], v[110:113]
	v_mfma_f32_16x16x32_bf16 v[106:109], v[144:147], v[210:213], v[106:109]
	v_mfma_f32_16x16x32_bf16 v[94:97], v[136:139], v[218:221], v[94:97]
	v_mfma_f32_16x16x32_bf16 v[90:93], v[144:147], v[218:221], v[90:93]
	v_mfma_f32_16x16x32_bf16 v[78:81], v[136:139], v[226:229], v[78:81]
	v_mfma_f32_16x16x32_bf16 v[74:77], v[144:147], v[226:229], v[74:77]
	v_mfma_f32_16x16x32_bf16 v[126:129], v[140:143], v[206:209], v[126:129]
	v_mfma_f32_16x16x32_bf16 v[122:125], v[154:157], v[206:209], v[122:125]
	v_mfma_f32_16x16x32_bf16 v[110:113], v[140:143], v[214:217], v[110:113]
	v_mfma_f32_16x16x32_bf16 v[106:109], v[154:157], v[214:217], v[106:109]
	v_mfma_f32_16x16x32_bf16 v[94:97], v[140:143], v[222:225], v[94:97]
	v_mfma_f32_16x16x32_bf16 v[90:93], v[154:157], v[222:225], v[90:93]
	v_mfma_f32_16x16x32_bf16 v[78:81], v[140:143], v[230:233], v[78:81]
	v_mfma_f32_16x16x32_bf16 v[74:77], v[154:157], v[230:233], v[74:77]
	s_setprio 0
	s_setprio 1
	v_mfma_f32_16x16x32_bf16 v[118:121], v[166:169], v[202:205], v[118:121]
	v_mfma_f32_16x16x32_bf16 v[114:117], v[174:177], v[202:205], v[114:117]
	v_mfma_f32_16x16x32_bf16 v[102:105], v[166:169], v[210:213], v[102:105]
	v_mfma_f32_16x16x32_bf16 v[98:101], v[174:177], v[210:213], v[98:101]
	v_mfma_f32_16x16x32_bf16 v[86:89], v[166:169], v[218:221], v[86:89]
	v_mfma_f32_16x16x32_bf16 v[82:85], v[174:177], v[218:221], v[82:85]
	v_mfma_f32_16x16x32_bf16 v[70:73], v[166:169], v[226:229], v[70:73]
	v_mfma_f32_16x16x32_bf16 v[66:69], v[174:177], v[226:229], v[66:69]
	v_mfma_f32_16x16x32_bf16 v[118:121], v[170:173], v[206:209], v[118:121]
	v_mfma_f32_16x16x32_bf16 v[114:117], v[198:201], v[206:209], v[114:117]
	v_mfma_f32_16x16x32_bf16 v[102:105], v[170:173], v[214:217], v[102:105]
	v_mfma_f32_16x16x32_bf16 v[98:101], v[198:201], v[214:217], v[98:101]
	v_mfma_f32_16x16x32_bf16 v[86:89], v[170:173], v[222:225], v[86:89]
	v_mfma_f32_16x16x32_bf16 v[82:85], v[198:201], v[222:225], v[82:85]
	v_mfma_f32_16x16x32_bf16 v[70:73], v[170:173], v[230:233], v[70:73]
	v_mfma_f32_16x16x32_bf16 v[66:69], v[198:201], v[230:233], v[66:69]
	s_setprio 0
	s_barrier
	s_add_i32 s28, s57, s43
	v_lshl_add_u64 v[148:149], v[148:149], 0, s[88:89]
	s_mov_b32 m0, s28
	ds_read_b128 v[202:205], v153 offset:49152
	ds_read_b128 v[206:209], v153 offset:50176
	ds_read_b128 v[210:213], v153 offset:51200
	ds_read_b128 v[214:217], v153 offset:52224
	ds_read_b128 v[218:221], v153 offset:53248
	ds_read_b128 v[222:225], v153 offset:54272
	ds_read_b128 v[226:229], v153 offset:55296
	ds_read_b128 v[230:233], v153 offset:56320
	global_load_lds_dwordx4 v[148:149], off
	s_add_i32 m0, s28, 0x2000
	s_add_u32 s28, s34, 0x100080
	v_lshl_add_u64 v[148:149], v[158:159], 0, s[88:89]
	s_addc_u32 s29, s35, 0
	s_add_i32 s34, s58, s43
	global_load_lds_dwordx4 v[148:149], off
	s_mov_b32 m0, s34
	s_nop 0
	global_load_lds_dwordx4 v0, s[28:29]
	s_add_i32 m0, s34, 0x2000
	s_nop 0
	global_load_lds_dwordx4 v130, s[28:29]
	v_lshl_add_u64 v[148:149], v[162:163], 0, s[88:89]
	s_mov_b32 m0, s49
	s_nop 0
	global_load_lds_dwordx4 v[148:149], off
	v_lshl_add_u64 v[148:149], v[164:165], 0, s[88:89]
	s_mov_b32 m0, s50
	s_nop 0
	global_load_lds_dwordx4 v[148:149], off
	s_waitcnt vmcnt(8)
	s_waitcnt lgkmcnt(0)
	s_barrier
	s_setprio 1
	s_waitcnt lgkmcnt(0)
	v_mfma_f32_16x16x32_bf16 v[62:65], v[136:139], v[202:205], v[62:65]
	v_mfma_f32_16x16x32_bf16 v[58:61], v[144:147], v[202:205], v[58:61]
	v_mfma_f32_16x16x32_bf16 v[46:49], v[136:139], v[210:213], v[46:49]
	v_mfma_f32_16x16x32_bf16 v[42:45], v[144:147], v[210:213], v[42:45]
	v_mfma_f32_16x16x32_bf16 v[30:33], v[136:139], v[218:221], v[30:33]
	v_mfma_f32_16x16x32_bf16 v[26:29], v[144:147], v[218:221], v[26:29]
	v_mfma_f32_16x16x32_bf16 v[14:17], v[136:139], v[226:229], v[14:17]
	v_mfma_f32_16x16x32_bf16 v[10:13], v[144:147], v[226:229], v[10:13]
	v_mfma_f32_16x16x32_bf16 v[62:65], v[140:143], v[206:209], v[62:65]
	v_mfma_f32_16x16x32_bf16 v[58:61], v[154:157], v[206:209], v[58:61]
	v_mfma_f32_16x16x32_bf16 v[46:49], v[140:143], v[214:217], v[46:49]
	v_mfma_f32_16x16x32_bf16 v[42:45], v[154:157], v[214:217], v[42:45]
	v_mfma_f32_16x16x32_bf16 v[30:33], v[140:143], v[222:225], v[30:33]
	v_mfma_f32_16x16x32_bf16 v[26:29], v[154:157], v[222:225], v[26:29]
	v_mfma_f32_16x16x32_bf16 v[14:17], v[140:143], v[230:233], v[14:17]
	v_mfma_f32_16x16x32_bf16 v[10:13], v[154:157], v[230:233], v[10:13]
	s_setprio 0
	s_setprio 1
	v_mfma_f32_16x16x32_bf16 v[54:57], v[166:169], v[202:205], v[54:57]
	v_mfma_f32_16x16x32_bf16 v[50:53], v[174:177], v[202:205], v[50:53]
	v_mfma_f32_16x16x32_bf16 v[38:41], v[166:169], v[210:213], v[38:41]
	v_mfma_f32_16x16x32_bf16 v[34:37], v[174:177], v[210:213], v[34:37]
	v_mfma_f32_16x16x32_bf16 v[22:25], v[166:169], v[218:221], v[22:25]
	v_mfma_f32_16x16x32_bf16 v[18:21], v[174:177], v[218:221], v[18:21]
	v_mfma_f32_16x16x32_bf16 v[6:9], v[166:169], v[226:229], v[6:9]
	v_mfma_f32_16x16x32_bf16 v[2:5], v[174:177], v[226:229], v[2:5]
	v_mfma_f32_16x16x32_bf16 v[54:57], v[170:173], v[206:209], v[54:57]
	v_mfma_f32_16x16x32_bf16 v[50:53], v[198:201], v[206:209], v[50:53]
	v_mfma_f32_16x16x32_bf16 v[38:41], v[170:173], v[214:217], v[38:41]
	v_mfma_f32_16x16x32_bf16 v[34:37], v[198:201], v[214:217], v[34:37]
	v_mfma_f32_16x16x32_bf16 v[22:25], v[170:173], v[222:225], v[22:25]
	v_mfma_f32_16x16x32_bf16 v[18:21], v[198:201], v[222:225], v[18:21]
	v_mfma_f32_16x16x32_bf16 v[6:9], v[170:173], v[230:233], v[6:9]
	v_mfma_f32_16x16x32_bf16 v[2:5], v[198:201], v[230:233], v[2:5]
	s_setprio 0
	s_barrier
	s_add_i32 s56, s56, 2
	s_add_u32 s54, s54, 0x100
	s_addc_u32 s55, s55, 0
	s_cmp_gt_u32 s56, 61
	s_mov_b64 s[28:29], s[30:31]
	s_cbranch_scc0 .LBB0_1342
	s_and_b64 vcc, exec, s[16:17]
	s_cbranch_vccz .LBB0_1345
	s_barrier
